# K-loop DMA issue split: 4 pieces after mid-step barrier, 4 in next sub-step, one per two MFMAs, all 9 GEMM loops
# speedup vs baseline: 1.0820x; 1.0104x over previous
; DI f32x16 mfma(bf16x8 a, bf16x8 b, f32x16 c) { return __builtin_amdgcn_mfma_f32_32x32x16_bf16(a, b, c, 0, 0, 0); }
; template <int BK> DI int swz(int row) { constexpr int CPR = BK / 8; return (row / (16 / CPR)) % CPR; }
; DI void wait_vm0() { asm volatile("s_waitcnt vmcnt(0)" ::: "memory"); }
;   DI void pre(int grow0, int gcol0, int lane, int w, char* lds) { xpass(0, grow0, gcol0, lane, w, lds); }
;     ...
;   for (int kt = 0; kt < nk; ++kt) {
;     char* cur = lds + (kt & 1) * STG; char* nxt = lds + ((kt + 1) & 1) * STG;
;     const bool more = kt + 1 < nk;
;     const bf16_t* An = Ag + (kt + 1) * BK; const bf16_t* Bn = Bg + (kt + 1) * BK;
;     if (!more) epi.pre(row0 + wm * 64, col0 + wn * (32 * NTW), lane, w, lds);
;     bf16x8 fa[2][2], fb[2][NTW];
; #pragma unroll
;     for (int mt = 0; mt < 2; ++mt) { int row = wm * 64 + mt * 32 + l31; fa[0][mt] = *(const bf16x8*)(cur + row * (BK * 2) + ((hh ^ swz<BK>(row)) << 4)); }
; #pragma unroll
;     for (int nt = 0; nt < NTW; ++nt) { int row = wn * (32 * NTW) + nt * 32 + l31; fb[0][nt] = *(const bf16x8*)(cur + ABYTES + row * (BK * 2) + ((hh ^ swz<BK>(row)) << 4)); }
; #pragma unroll
;     for (int kk = 0; kk < NKK; ++kk) {
;       if (kk + 1 < NKK) {
;         const int ch = (kk + 1) * 2 + hh;
; #pragma unroll
;         for (int mt = 0; mt < 2; ++mt) { int row = wm * 64 + mt * 32 + l31; fa[(kk + 1) & 1][mt] = *(const bf16x8*)(cur + row * (BK * 2) + ((ch ^ swz<BK>(row)) << 4)); }
; #pragma unroll
;         for (int nt = 0; nt < NTW; ++nt) { int row = wn * (32 * NTW) + nt * 32 + l31; fb[(kk + 1) & 1][nt] = *(const bf16x8*)(cur + ABYTES + row * (BK * 2) + ((ch ^ swz<BK>(row)) << 4)); }
;       }
;       if (more) {
; #pragma unroll
;         for (int q = 0; q < PPK; ++q) {
;           const int pi = kk * PPK + q;
;           if (pi < NPA) stage_piece<BM, BK>(An, lda, nxt, tid, pi, wv);
;           else if (pi < NP) stage_piece<BN, BK>(Bn, ldb, nxt + ABYTES, tid, pi - NPA, wv);
;         }
;       }
;       __builtin_amdgcn_s_setprio(1);
; #pragma unroll
;       for (int mt = 0; mt < 2; ++mt)
; #pragma unroll
;         for (int nt = 0; nt < NTW; ++nt) acc[mt][nt] = mfma(fa[kk & 1][mt], fb[kk & 1][nt], acc[mt][nt]);
;       __builtin_amdgcn_s_setprio(0);
;       __builtin_amdgcn_sched_barrier(0);
;     }
;     wait_vm0();
;     __syncthreads();
.LBB0_173:
	s_and_b32 s30, s3, 0x10000
	s_xor_b32 s100, s30, 0x10000
	v_add3_u32 v194, s100, v136, v166
	v_add3_u32 v198, s100, v144, v167
	ds_read_b128 v[194:197], v194
	v_add3_u32 v202, s100, v145, v161
	ds_read_b128 v[198:201], v198
	v_add3_u32 v206, s100, v152, v163
	ds_read_b128 v[202:205], v202 offset:32768
	v_add3_u32 v210, s100, v155, v159
	ds_read_b128 v[206:209], v206 offset:32768
	v_add3_u32 v226, s100, v158, v160
	ds_read_b128 v[210:213], v210 offset:32768
	ds_read_b128 v[226:229], v226 offset:32768
	s_waitcnt lgkmcnt(6)
	s_add_i32 m0, s31, 0x8000
	v_lshl_add_u64 v[232:233], v[230:231], 0, s[28:29]
	v_mfma_f32_32x32x16_bf16 v[114:129], v[170:173], v[178:181], v[114:129]
	global_load_lds_dwordx4 v[232:233], off
	s_add_i32 m0, s31, 0xa000
	v_lshl_add_u64 v[232:233], v[230:231], 0, s[24:25]
	v_mfma_f32_32x32x16_bf16 v[98:113], v[170:173], v[182:185], v[98:113]
	v_mfma_f32_32x32x16_bf16 v[82:97], v[170:173], v[186:189], v[82:97]
	global_load_lds_dwordx4 v[232:233], off
	s_add_i32 m0, s31, 0xc000
	v_lshl_add_u64 v[232:233], v[230:231], 0, s[26:27]
	v_mfma_f32_32x32x16_bf16 v[66:81], v[170:173], v[190:193], v[66:81]
	v_mfma_f32_32x32x16_bf16 v[50:65], v[174:177], v[178:181], v[50:65]
	global_load_lds_dwordx4 v[232:233], off
	s_add_i32 m0, s31, 0xe000
	v_lshl_add_u64 v[232:233], v[230:231], 0, s[38:39]
	v_mfma_f32_32x32x16_bf16 v[34:49], v[174:177], v[182:185], v[34:49]
	v_mfma_f32_32x32x16_bf16 v[18:33], v[174:177], v[186:189], v[18:33]
	global_load_lds_dwordx4 v[232:233], off
	v_mfma_f32_32x32x16_bf16 v[2:17], v[174:177], v[190:193], v[2:17]
	v_add3_u32 v170, s100, v136, v153
	v_add3_u32 v174, s100, v144, v154
	ds_read_b128 v[170:173], v170
	v_add3_u32 v178, s100, v145, v149
	ds_read_b128 v[174:177], v174
	v_add3_u32 v182, s100, v152, v150
	ds_read_b128 v[178:181], v178 offset:32768
	v_add3_u32 v186, s100, v155, v147
	ds_read_b128 v[182:185], v182 offset:32768
	v_add3_u32 v190, s100, v158, v148
	ds_read_b128 v[186:189], v186 offset:32768
	ds_read_b128 v[190:193], v190 offset:32768
	s_waitcnt lgkmcnt(6)
	v_mfma_f32_32x32x16_bf16 v[114:129], v[194:197], v[202:205], v[114:129]
	v_mfma_f32_32x32x16_bf16 v[98:113], v[194:197], v[206:209], v[98:113]
	v_mfma_f32_32x32x16_bf16 v[82:97], v[194:197], v[210:213], v[82:97]
	v_mfma_f32_32x32x16_bf16 v[66:81], v[194:197], v[226:229], v[66:81]
	v_mfma_f32_32x32x16_bf16 v[50:65], v[198:201], v[202:205], v[50:65]
	v_mfma_f32_32x32x16_bf16 v[34:49], v[198:201], v[206:209], v[34:49]
	v_mfma_f32_32x32x16_bf16 v[18:33], v[198:201], v[210:213], v[18:33]
	v_mfma_f32_32x32x16_bf16 v[2:17], v[198:201], v[226:229], v[2:17]
	v_add3_u32 v194, s100, v136, v141
	v_add3_u32 v198, s100, v144, v142
	ds_read_b128 v[194:197], v194
	v_add3_u32 v202, s100, v145, v139
	ds_read_b128 v[198:201], v198
	v_add3_u32 v206, s100, v152, v140
	ds_read_b128 v[202:205], v202 offset:32768
	v_add3_u32 v210, s100, v155, v137
	ds_read_b128 v[206:209], v206 offset:32768
	v_add3_u32 v226, s100, v158, v138
	ds_read_b128 v[210:213], v210 offset:32768
	ds_read_b128 v[226:229], v226 offset:32768
	s_waitcnt lgkmcnt(6)
	v_mfma_f32_32x32x16_bf16 v[114:129], v[170:173], v[178:181], v[114:129]
	v_mfma_f32_32x32x16_bf16 v[98:113], v[170:173], v[182:185], v[98:113]
	v_mfma_f32_32x32x16_bf16 v[82:97], v[170:173], v[186:189], v[82:97]
	v_mfma_f32_32x32x16_bf16 v[66:81], v[170:173], v[190:193], v[66:81]
	v_mfma_f32_32x32x16_bf16 v[50:65], v[174:177], v[178:181], v[50:65]
	v_mfma_f32_32x32x16_bf16 v[34:49], v[174:177], v[182:185], v[34:49]
	v_mfma_f32_32x32x16_bf16 v[18:33], v[174:177], v[186:189], v[18:33]
	v_mfma_f32_32x32x16_bf16 v[2:17], v[174:177], v[190:193], v[2:17]
	s_add_u32 s6, s6, 0x80
	s_addc_u32 s7, s7, 0
	s_add_i32 s3, s3, 0x10000
	s_waitcnt vmcnt(0) lgkmcnt(0)
	s_barrier
	v_add3_u32 v170, s30, v136, v143
	v_add3_u32 v174, s30, v144, v146
	ds_read_b128 v[170:173], v170
	v_add3_u32 v178, s30, v145, v151
	ds_read_b128 v[174:177], v174
	v_add3_u32 v182, s30, v152, v156
	ds_read_b128 v[178:181], v178 offset:32768
	v_add3_u32 v186, s30, v155, v157
	ds_read_b128 v[182:185], v182 offset:32768
	v_add3_u32 v190, s30, v158, v168
	ds_read_b128 v[186:189], v186 offset:32768
	ds_read_b128 v[190:193], v190 offset:32768
	s_cmpk_lg_i32 s6, 0x780
	s_cbranch_scc0 .Lk173_exit
	s_add_i32 s31, s100, s2
	v_lshl_add_u64 v[214:215], v[132:133], 0, s[6:7]
	v_lshl_add_u64 v[230:231], v[130:131], 0, s[6:7]
	s_mov_b32 m0, s31
	v_lshl_add_u64 v[232:233], v[214:215], 0, s[28:29]
	v_mfma_f32_32x32x16_bf16 v[114:129], v[194:197], v[202:205], v[114:129]
	global_load_lds_dwordx4 v[232:233], off
	s_add_i32 m0, s31, 0x2000
	v_lshl_add_u64 v[232:233], v[214:215], 0, s[24:25]
	v_mfma_f32_32x32x16_bf16 v[98:113], v[194:197], v[206:209], v[98:113]
	v_mfma_f32_32x32x16_bf16 v[82:97], v[194:197], v[210:213], v[82:97]
	global_load_lds_dwordx4 v[232:233], off
	s_add_i32 m0, s31, 0x4000
	v_lshl_add_u64 v[232:233], v[214:215], 0, s[26:27]
	v_mfma_f32_32x32x16_bf16 v[66:81], v[194:197], v[226:229], v[66:81]
	v_mfma_f32_32x32x16_bf16 v[50:65], v[198:201], v[202:205], v[50:65]
	global_load_lds_dwordx4 v[232:233], off
	s_add_i32 m0, s31, 0x6000
	v_lshl_add_u64 v[232:233], v[214:215], 0, s[38:39]
	v_mfma_f32_32x32x16_bf16 v[34:49], v[198:201], v[206:209], v[34:49]
	v_mfma_f32_32x32x16_bf16 v[18:33], v[198:201], v[210:213], v[18:33]
	global_load_lds_dwordx4 v[232:233], off
	v_mfma_f32_32x32x16_bf16 v[2:17], v[198:201], v[226:229], v[2:17]
	s_branch .LBB0_173

; DI f32x16 mfma(bf16x8 a, bf16x8 b, f32x16 c) { return __builtin_amdgcn_mfma_f32_32x32x16_bf16(a, b, c, 0, 0, 0); }
; template <int BK> DI int swz(int row) { constexpr int CPR = BK / 8; return (row / (16 / CPR)) % CPR; }
; DI void wait_vm0() { asm volatile("s_waitcnt vmcnt(0)" ::: "memory"); }
;   DI void pre(int grow0, int gcol0, int lane, int w, char* lds) { xpass(0, grow0, gcol0, lane, w, lds); }
;     ...
;   for (int kt = 0; kt < nk; ++kt) {
;     char* cur = lds + (kt & 1) * STG; char* nxt = lds + ((kt + 1) & 1) * STG;
;     const bool more = kt + 1 < nk;
;     const bf16_t* An = Ag + (kt + 1) * BK; const bf16_t* Bn = Bg + (kt + 1) * BK;
;     if (!more) epi.pre(row0 + wm * 64, col0 + wn * (32 * NTW), lane, w, lds);
;     bf16x8 fa[2][2], fb[2][NTW];
; #pragma unroll
;     for (int mt = 0; mt < 2; ++mt) { int row = wm * 64 + mt * 32 + l31; fa[0][mt] = *(const bf16x8*)(cur + row * (BK * 2) + ((hh ^ swz<BK>(row)) << 4)); }
; #pragma unroll
;     for (int nt = 0; nt < NTW; ++nt) { int row = wn * (32 * NTW) + nt * 32 + l31; fb[0][nt] = *(const bf16x8*)(cur + ABYTES + row * (BK * 2) + ((hh ^ swz<BK>(row)) << 4)); }
; #pragma unroll
;     for (int kk = 0; kk < NKK; ++kk) {
;       if (kk + 1 < NKK) {
;         const int ch = (kk + 1) * 2 + hh;
; #pragma unroll
;         for (int mt = 0; mt < 2; ++mt) { int row = wm * 64 + mt * 32 + l31; fa[(kk + 1) & 1][mt] = *(const bf16x8*)(cur + row * (BK * 2) + ((ch ^ swz<BK>(row)) << 4)); }
; #pragma unroll
;         for (int nt = 0; nt < NTW; ++nt) { int row = wn * (32 * NTW) + nt * 32 + l31; fb[(kk + 1) & 1][nt] = *(const bf16x8*)(cur + ABYTES + row * (BK * 2) + ((ch ^ swz<BK>(row)) << 4)); }
;       }
;       if (more) {
; #pragma unroll
;         for (int q = 0; q < PPK; ++q) {
;           const int pi = kk * PPK + q;
;           if (pi < NPA) stage_piece<BM, BK>(An, lda, nxt, tid, pi, wv);
;           else if (pi < NP) stage_piece<BN, BK>(Bn, ldb, nxt + ABYTES, tid, pi - NPA, wv);
;         }
;       }
;       __builtin_amdgcn_s_setprio(1);
; #pragma unroll
;       for (int mt = 0; mt < 2; ++mt)
; #pragma unroll
;         for (int nt = 0; nt < NTW; ++nt) acc[mt][nt] = mfma(fa[kk & 1][mt], fb[kk & 1][nt], acc[mt][nt]);
;       __builtin_amdgcn_s_setprio(0);
;       __builtin_amdgcn_sched_barrier(0);
;     }
;     wait_vm0();
;     __syncthreads();
.LBB0_284:
	s_and_b32 s35, s7, 0x10000
	s_xor_b32 s100, s35, 0x10000
	v_add3_u32 v190, s100, v140, v161
	v_add3_u32 v194, s100, v142, v163
	ds_read_b128 v[190:193], v190
	v_add3_u32 v198, s100, v143, v159
	ds_read_b128 v[194:197], v194
	v_add3_u32 v202, s100, v152, v160
	ds_read_b128 v[198:201], v198 offset:32768
	v_add3_u32 v206, s100, v153, v157
	ds_read_b128 v[202:205], v202 offset:32768
	v_add3_u32 v210, s100, v156, v158
	ds_read_b128 v[206:209], v206 offset:32768
	ds_read_b128 v[210:213], v210 offset:32768
	s_waitcnt lgkmcnt(6)
	s_add_i32 m0, s34, 0x8000
	v_lshl_add_u64 v[228:229], v[226:227], 0, s[28:29]
	v_mfma_f32_32x32x16_bf16 v[114:129], v[166:169], v[174:177], v[114:129]
	global_load_lds_dwordx4 v[228:229], off
	s_add_i32 m0, s34, 0xa000
	v_lshl_add_u64 v[228:229], v[226:227], 0, s[24:25]
	v_mfma_f32_32x32x16_bf16 v[98:113], v[166:169], v[178:181], v[98:113]
	v_mfma_f32_32x32x16_bf16 v[82:97], v[166:169], v[182:185], v[82:97]
	global_load_lds_dwordx4 v[228:229], off
	s_add_i32 m0, s34, 0xc000
	v_lshl_add_u64 v[228:229], v[226:227], 0, s[26:27]
	v_mfma_f32_32x32x16_bf16 v[66:81], v[166:169], v[186:189], v[66:81]
	v_mfma_f32_32x32x16_bf16 v[50:65], v[170:173], v[174:177], v[50:65]
	global_load_lds_dwordx4 v[228:229], off
	s_add_i32 m0, s34, 0xe000
	v_lshl_add_u64 v[228:229], v[226:227], 0, s[38:39]
	v_mfma_f32_32x32x16_bf16 v[34:49], v[170:173], v[178:181], v[34:49]
	v_mfma_f32_32x32x16_bf16 v[18:33], v[170:173], v[182:185], v[18:33]
	global_load_lds_dwordx4 v[228:229], off
	v_mfma_f32_32x32x16_bf16 v[2:17], v[170:173], v[186:189], v[2:17]
	v_add3_u32 v166, s100, v140, v149
	v_add3_u32 v170, s100, v142, v150
	ds_read_b128 v[166:169], v166
	v_add3_u32 v174, s100, v143, v147
	ds_read_b128 v[170:173], v170
	v_add3_u32 v178, s100, v152, v148
	ds_read_b128 v[174:177], v174 offset:32768
	v_add3_u32 v182, s100, v153, v145
	ds_read_b128 v[178:181], v178 offset:32768
	v_add3_u32 v186, s100, v156, v146
	ds_read_b128 v[182:185], v182 offset:32768
	ds_read_b128 v[186:189], v186 offset:32768
	s_waitcnt lgkmcnt(6)
	v_mfma_f32_32x32x16_bf16 v[114:129], v[190:193], v[198:201], v[114:129]
	v_mfma_f32_32x32x16_bf16 v[98:113], v[190:193], v[202:205], v[98:113]
	v_mfma_f32_32x32x16_bf16 v[82:97], v[190:193], v[206:209], v[82:97]
	v_mfma_f32_32x32x16_bf16 v[66:81], v[190:193], v[210:213], v[66:81]
	v_mfma_f32_32x32x16_bf16 v[50:65], v[194:197], v[198:201], v[50:65]
	v_mfma_f32_32x32x16_bf16 v[34:49], v[194:197], v[202:205], v[34:49]
	v_mfma_f32_32x32x16_bf16 v[18:33], v[194:197], v[206:209], v[18:33]
	v_mfma_f32_32x32x16_bf16 v[2:17], v[194:197], v[210:213], v[2:17]
	v_add3_u32 v190, s100, v140, v138
	v_add3_u32 v194, s100, v142, v139
	ds_read_b128 v[190:193], v190
	v_add3_u32 v198, s100, v143, v136
	ds_read_b128 v[194:197], v194
	v_add3_u32 v202, s100, v152, v137
	ds_read_b128 v[198:201], v198 offset:32768
	v_add3_u32 v206, s100, v153, v134
	ds_read_b128 v[202:205], v202 offset:32768
	v_add3_u32 v210, s100, v156, v135
	ds_read_b128 v[206:209], v206 offset:32768
	ds_read_b128 v[210:213], v210 offset:32768
	s_waitcnt lgkmcnt(6)
	v_mfma_f32_32x32x16_bf16 v[114:129], v[166:169], v[174:177], v[114:129]
	v_mfma_f32_32x32x16_bf16 v[98:113], v[166:169], v[178:181], v[98:113]
	v_mfma_f32_32x32x16_bf16 v[82:97], v[166:169], v[182:185], v[82:97]
	v_mfma_f32_32x32x16_bf16 v[66:81], v[166:169], v[186:189], v[66:81]
	v_mfma_f32_32x32x16_bf16 v[50:65], v[170:173], v[174:177], v[50:65]
	v_mfma_f32_32x32x16_bf16 v[34:49], v[170:173], v[178:181], v[34:49]
	v_mfma_f32_32x32x16_bf16 v[18:33], v[170:173], v[182:185], v[18:33]
	v_mfma_f32_32x32x16_bf16 v[2:17], v[170:173], v[186:189], v[2:17]
	s_add_u32 s30, s30, 0x80
	s_addc_u32 s31, s31, 0
	s_add_i32 s7, s7, 0x10000
	s_waitcnt vmcnt(0) lgkmcnt(0)
	s_barrier
	v_add3_u32 v166, s35, v140, v141
	v_add3_u32 v170, s35, v142, v144
	ds_read_b128 v[166:169], v166
	v_add3_u32 v174, s35, v143, v151
	ds_read_b128 v[170:173], v170
	v_add3_u32 v178, s35, v152, v154
	ds_read_b128 v[174:177], v174 offset:32768
	v_add3_u32 v182, s35, v153, v155
	ds_read_b128 v[178:181], v178 offset:32768
	v_add3_u32 v186, s35, v156, v164
	ds_read_b128 v[182:185], v182 offset:32768
	ds_read_b128 v[186:189], v186 offset:32768
	s_cmpk_eq_i32 s30, 0x780
	s_cbranch_scc1 .Lk284_exit
	s_add_i32 s34, s100, s3
	v_lshl_add_u64 v[214:215], v[130:131], 0, s[30:31]
	v_lshl_add_u64 v[226:227], v[132:133], 0, s[30:31]
	s_mov_b32 m0, s34
	v_lshl_add_u64 v[228:229], v[214:215], 0, s[28:29]
	v_mfma_f32_32x32x16_bf16 v[114:129], v[190:193], v[198:201], v[114:129]
	global_load_lds_dwordx4 v[228:229], off
	s_add_i32 m0, s34, 0x2000
	v_lshl_add_u64 v[228:229], v[214:215], 0, s[24:25]
	v_mfma_f32_32x32x16_bf16 v[98:113], v[190:193], v[202:205], v[98:113]
	v_mfma_f32_32x32x16_bf16 v[82:97], v[190:193], v[206:209], v[82:97]
	global_load_lds_dwordx4 v[228:229], off
	s_add_i32 m0, s34, 0x4000
	v_lshl_add_u64 v[228:229], v[214:215], 0, s[26:27]
	v_mfma_f32_32x32x16_bf16 v[66:81], v[190:193], v[210:213], v[66:81]
	v_mfma_f32_32x32x16_bf16 v[50:65], v[194:197], v[198:201], v[50:65]
	global_load_lds_dwordx4 v[228:229], off
	s_add_i32 m0, s34, 0x6000
	v_lshl_add_u64 v[228:229], v[214:215], 0, s[38:39]
	v_mfma_f32_32x32x16_bf16 v[34:49], v[194:197], v[202:205], v[34:49]
	v_mfma_f32_32x32x16_bf16 v[18:33], v[194:197], v[206:209], v[18:33]
	global_load_lds_dwordx4 v[228:229], off
	v_mfma_f32_32x32x16_bf16 v[2:17], v[194:197], v[210:213], v[2:17]
	s_branch .LBB0_284

; DI f32x16 mfma(bf16x8 a, bf16x8 b, f32x16 c) { return __builtin_amdgcn_mfma_f32_32x32x16_bf16(a, b, c, 0, 0, 0); }
; template <int BK> DI int swz(int row) { constexpr int CPR = BK / 8; return (row / (16 / CPR)) % CPR; }
; DI void wait_vm0() { asm volatile("s_waitcnt vmcnt(0)" ::: "memory"); }
;   DI void pre(int grow0, int gcol0, int lane, int w, char* lds) { xpass(0, grow0, gcol0, lane, w, lds); }
;     ...
;   for (int kt = 0; kt < nk; ++kt) {
;     char* cur = lds + (kt & 1) * STG; char* nxt = lds + ((kt + 1) & 1) * STG;
;     const bool more = kt + 1 < nk;
;     const bf16_t* An = Ag + (kt + 1) * BK; const bf16_t* Bn = Bg + (kt + 1) * BK;
;     if (!more) epi.pre(row0 + wm * 64, col0 + wn * (32 * NTW), lane, w, lds);
;     bf16x8 fa[2][2], fb[2][NTW];
; #pragma unroll
;     for (int mt = 0; mt < 2; ++mt) { int row = wm * 64 + mt * 32 + l31; fa[0][mt] = *(const bf16x8*)(cur + row * (BK * 2) + ((hh ^ swz<BK>(row)) << 4)); }
; #pragma unroll
;     for (int nt = 0; nt < NTW; ++nt) { int row = wn * (32 * NTW) + nt * 32 + l31; fb[0][nt] = *(const bf16x8*)(cur + ABYTES + row * (BK * 2) + ((hh ^ swz<BK>(row)) << 4)); }
; #pragma unroll
;     for (int kk = 0; kk < NKK; ++kk) {
;       if (kk + 1 < NKK) {
;         const int ch = (kk + 1) * 2 + hh;
; #pragma unroll
;         for (int mt = 0; mt < 2; ++mt) { int row = wm * 64 + mt * 32 + l31; fa[(kk + 1) & 1][mt] = *(const bf16x8*)(cur + row * (BK * 2) + ((ch ^ swz<BK>(row)) << 4)); }
; #pragma unroll
;         for (int nt = 0; nt < NTW; ++nt) { int row = wn * (32 * NTW) + nt * 32 + l31; fb[(kk + 1) & 1][nt] = *(const bf16x8*)(cur + ABYTES + row * (BK * 2) + ((ch ^ swz<BK>(row)) << 4)); }
;       }
;       if (more) {
; #pragma unroll
;         for (int q = 0; q < PPK; ++q) {
;           const int pi = kk * PPK + q;
;           if (pi < NPA) stage_piece<BM, BK>(An, lda, nxt, tid, pi, wv);
;           else if (pi < NP) stage_piece<BN, BK>(Bn, ldb, nxt + ABYTES, tid, pi - NPA, wv);
;         }
;       }
;       __builtin_amdgcn_s_setprio(1);
; #pragma unroll
;       for (int mt = 0; mt < 2; ++mt)
; #pragma unroll
;         for (int nt = 0; nt < NTW; ++nt) acc[mt][nt] = mfma(fa[kk & 1][mt], fb[kk & 1][nt], acc[mt][nt]);
;       __builtin_amdgcn_s_setprio(0);
;       __builtin_amdgcn_sched_barrier(0);
;     }
;     wait_vm0();
;     __syncthreads();
.LBB0_292:
	s_and_b32 s30, s3, 0x10000
	s_xor_b32 s100, s30, 0x10000
	v_add3_u32 v194, s100, v136, v164
	v_add3_u32 v198, s100, v144, v166
	ds_read_b128 v[194:197], v194
	v_add3_u32 v202, s100, v145, v161
	ds_read_b128 v[198:201], v198
	v_add3_u32 v206, s100, v152, v163
	ds_read_b128 v[202:205], v202 offset:32768
	v_add3_u32 v210, s100, v155, v159
	ds_read_b128 v[206:209], v206 offset:32768
	v_add3_u32 v226, s100, v158, v160
	ds_read_b128 v[210:213], v210 offset:32768
	ds_read_b128 v[226:229], v226 offset:32768
	s_waitcnt lgkmcnt(6)
	s_add_i32 m0, s31, 0x8000
	v_lshl_add_u64 v[232:233], v[230:231], 0, s[28:29]
	v_mfma_f32_32x32x16_bf16 v[114:129], v[170:173], v[178:181], v[114:129]
	global_load_lds_dwordx4 v[232:233], off
	s_add_i32 m0, s31, 0xa000
	v_lshl_add_u64 v[232:233], v[230:231], 0, s[36:37]
	v_mfma_f32_32x32x16_bf16 v[98:113], v[170:173], v[182:185], v[98:113]
	v_mfma_f32_32x32x16_bf16 v[82:97], v[170:173], v[186:189], v[82:97]
	global_load_lds_dwordx4 v[232:233], off
	s_add_i32 m0, s31, 0xc000
	v_lshl_add_u64 v[232:233], v[230:231], 0, s[40:41]
	v_mfma_f32_32x32x16_bf16 v[66:81], v[170:173], v[190:193], v[66:81]
	v_mfma_f32_32x32x16_bf16 v[50:65], v[174:177], v[178:181], v[50:65]
	global_load_lds_dwordx4 v[232:233], off
	s_add_i32 m0, s31, 0xe000
	v_lshl_add_u64 v[232:233], v[230:231], 0, s[42:43]
	v_mfma_f32_32x32x16_bf16 v[34:49], v[174:177], v[182:185], v[34:49]
	v_mfma_f32_32x32x16_bf16 v[18:33], v[174:177], v[186:189], v[18:33]
	global_load_lds_dwordx4 v[232:233], off
	v_mfma_f32_32x32x16_bf16 v[2:17], v[174:177], v[190:193], v[2:17]
	v_add3_u32 v170, s100, v136, v153
	v_add3_u32 v174, s100, v144, v154
	ds_read_b128 v[170:173], v170
	v_add3_u32 v178, s100, v145, v149
	ds_read_b128 v[174:177], v174
	v_add3_u32 v182, s100, v152, v150
	ds_read_b128 v[178:181], v178 offset:32768
	v_add3_u32 v186, s100, v155, v147
	ds_read_b128 v[182:185], v182 offset:32768
	v_add3_u32 v190, s100, v158, v148
	ds_read_b128 v[186:189], v186 offset:32768
	ds_read_b128 v[190:193], v190 offset:32768
	s_waitcnt lgkmcnt(6)
	v_mfma_f32_32x32x16_bf16 v[114:129], v[194:197], v[202:205], v[114:129]
	v_mfma_f32_32x32x16_bf16 v[98:113], v[194:197], v[206:209], v[98:113]
	v_mfma_f32_32x32x16_bf16 v[82:97], v[194:197], v[210:213], v[82:97]
	v_mfma_f32_32x32x16_bf16 v[66:81], v[194:197], v[226:229], v[66:81]
	v_mfma_f32_32x32x16_bf16 v[50:65], v[198:201], v[202:205], v[50:65]
	v_mfma_f32_32x32x16_bf16 v[34:49], v[198:201], v[206:209], v[34:49]
	v_mfma_f32_32x32x16_bf16 v[18:33], v[198:201], v[210:213], v[18:33]
	v_mfma_f32_32x32x16_bf16 v[2:17], v[198:201], v[226:229], v[2:17]
	v_add3_u32 v194, s100, v136, v141
	v_add3_u32 v198, s100, v144, v142
	ds_read_b128 v[194:197], v194
	v_add3_u32 v202, s100, v145, v139
	ds_read_b128 v[198:201], v198
	v_add3_u32 v206, s100, v152, v140
	ds_read_b128 v[202:205], v202 offset:32768
	v_add3_u32 v210, s100, v155, v137
	ds_read_b128 v[206:209], v206 offset:32768
	v_add3_u32 v226, s100, v158, v138
	ds_read_b128 v[210:213], v210 offset:32768
	ds_read_b128 v[226:229], v226 offset:32768
	s_waitcnt lgkmcnt(6)
	v_mfma_f32_32x32x16_bf16 v[114:129], v[170:173], v[178:181], v[114:129]
	v_mfma_f32_32x32x16_bf16 v[98:113], v[170:173], v[182:185], v[98:113]
	v_mfma_f32_32x32x16_bf16 v[82:97], v[170:173], v[186:189], v[82:97]
	v_mfma_f32_32x32x16_bf16 v[66:81], v[170:173], v[190:193], v[66:81]
	v_mfma_f32_32x32x16_bf16 v[50:65], v[174:177], v[178:181], v[50:65]
	v_mfma_f32_32x32x16_bf16 v[34:49], v[174:177], v[182:185], v[34:49]
	v_mfma_f32_32x32x16_bf16 v[18:33], v[174:177], v[186:189], v[18:33]
	v_mfma_f32_32x32x16_bf16 v[2:17], v[174:177], v[190:193], v[2:17]
	s_add_u32 s6, s6, 0x80
	s_addc_u32 s7, s7, 0
	s_add_i32 s3, s3, 0x10000
	s_waitcnt vmcnt(0) lgkmcnt(0)
	s_barrier
	v_add3_u32 v170, s30, v136, v143
	v_add3_u32 v174, s30, v144, v146
	ds_read_b128 v[170:173], v170
	v_add3_u32 v178, s30, v145, v151
	ds_read_b128 v[174:177], v174
	v_add3_u32 v182, s30, v152, v156
	ds_read_b128 v[178:181], v178 offset:32768
	v_add3_u32 v186, s30, v155, v157
	ds_read_b128 v[182:185], v182 offset:32768
	v_add3_u32 v190, s30, v158, v167
	ds_read_b128 v[186:189], v186 offset:32768
	ds_read_b128 v[190:193], v190 offset:32768
	s_cmpk_lg_i32 s6, 0x1580
	s_cbranch_scc0 .Lk292_exit
	s_add_i32 s31, s100, s2
	v_lshl_add_u64 v[214:215], v[132:133], 0, s[6:7]
	v_lshl_add_u64 v[230:231], v[130:131], 0, s[6:7]
	s_mov_b32 m0, s31
	v_lshl_add_u64 v[232:233], v[214:215], 0, s[28:29]
	v_mfma_f32_32x32x16_bf16 v[114:129], v[194:197], v[202:205], v[114:129]
	global_load_lds_dwordx4 v[232:233], off
	s_add_i32 m0, s31, 0x2000
	v_lshl_add_u64 v[232:233], v[214:215], 0, s[36:37]
	v_mfma_f32_32x32x16_bf16 v[98:113], v[194:197], v[206:209], v[98:113]
	v_mfma_f32_32x32x16_bf16 v[82:97], v[194:197], v[210:213], v[82:97]
	global_load_lds_dwordx4 v[232:233], off
	s_add_i32 m0, s31, 0x4000
	v_lshl_add_u64 v[232:233], v[214:215], 0, s[40:41]
	v_mfma_f32_32x32x16_bf16 v[66:81], v[194:197], v[226:229], v[66:81]
	v_mfma_f32_32x32x16_bf16 v[50:65], v[198:201], v[202:205], v[50:65]
	global_load_lds_dwordx4 v[232:233], off
	s_add_i32 m0, s31, 0x6000
	v_lshl_add_u64 v[232:233], v[214:215], 0, s[42:43]
	v_mfma_f32_32x32x16_bf16 v[34:49], v[198:201], v[206:209], v[34:49]
	v_mfma_f32_32x32x16_bf16 v[18:33], v[198:201], v[210:213], v[18:33]
	global_load_lds_dwordx4 v[232:233], off
	v_mfma_f32_32x32x16_bf16 v[2:17], v[198:201], v[226:229], v[2:17]
	s_branch .LBB0_292

; DI f32x16 mfma(bf16x8 a, bf16x8 b, f32x16 c) { return __builtin_amdgcn_mfma_f32_32x32x16_bf16(a, b, c, 0, 0, 0); }
; template <int BK> DI int swz(int row) { constexpr int CPR = BK / 8; return (row / (16 / CPR)) % CPR; }
; DI void wait_vm0() { asm volatile("s_waitcnt vmcnt(0)" ::: "memory"); }
;   DI void pre(int grow0, int gcol0, int lane, int w, char* lds) { xpass(0, grow0, gcol0, lane, w, lds); }
;     ...
;   for (int kt = 0; kt < nk; ++kt) {
;     char* cur = lds + (kt & 1) * STG; char* nxt = lds + ((kt + 1) & 1) * STG;
;     const bool more = kt + 1 < nk;
;     const bf16_t* An = Ag + (kt + 1) * BK; const bf16_t* Bn = Bg + (kt + 1) * BK;
;     if (!more) epi.pre(row0 + wm * 64, col0 + wn * (32 * NTW), lane, w, lds);
;     bf16x8 fa[2][2], fb[2][NTW];
; #pragma unroll
;     for (int mt = 0; mt < 2; ++mt) { int row = wm * 64 + mt * 32 + l31; fa[0][mt] = *(const bf16x8*)(cur + row * (BK * 2) + ((hh ^ swz<BK>(row)) << 4)); }
; #pragma unroll
;     for (int nt = 0; nt < NTW; ++nt) { int row = wn * (32 * NTW) + nt * 32 + l31; fb[0][nt] = *(const bf16x8*)(cur + ABYTES + row * (BK * 2) + ((hh ^ swz<BK>(row)) << 4)); }
; #pragma unroll
;     for (int kk = 0; kk < NKK; ++kk) {
;       if (kk + 1 < NKK) {
;         const int ch = (kk + 1) * 2 + hh;
; #pragma unroll
;         for (int mt = 0; mt < 2; ++mt) { int row = wm * 64 + mt * 32 + l31; fa[(kk + 1) & 1][mt] = *(const bf16x8*)(cur + row * (BK * 2) + ((ch ^ swz<BK>(row)) << 4)); }
; #pragma unroll
;         for (int nt = 0; nt < NTW; ++nt) { int row = wn * (32 * NTW) + nt * 32 + l31; fb[(kk + 1) & 1][nt] = *(const bf16x8*)(cur + ABYTES + row * (BK * 2) + ((ch ^ swz<BK>(row)) << 4)); }
;       }
;       if (more) {
; #pragma unroll
;         for (int q = 0; q < PPK; ++q) {
;           const int pi = kk * PPK + q;
;           if (pi < NPA) stage_piece<BM, BK>(An, lda, nxt, tid, pi, wv);
;           else if (pi < NP) stage_piece<BN, BK>(Bn, ldb, nxt + ABYTES, tid, pi - NPA, wv);
;         }
;       }
;       __builtin_amdgcn_s_setprio(1);
; #pragma unroll
;       for (int mt = 0; mt < 2; ++mt)
; #pragma unroll
;         for (int nt = 0; nt < NTW; ++nt) acc[mt][nt] = mfma(fa[kk & 1][mt], fb[kk & 1][nt], acc[mt][nt]);
;       __builtin_amdgcn_s_setprio(0);
;       __builtin_amdgcn_sched_barrier(0);
;     }
;     wait_vm0();
;     __syncthreads();
.LBB0_382:
	s_and_b32 s42, s7, 0x10000
	s_xor_b32 s100, s42, 0x10000
	v_add3_u32 v190, s100, v140, v161
	v_add3_u32 v194, s100, v142, v163
	ds_read_b128 v[190:193], v190
	v_add3_u32 v198, s100, v143, v159
	ds_read_b128 v[194:197], v194
	v_add3_u32 v202, s100, v152, v160
	ds_read_b128 v[198:201], v198 offset:32768
	v_add3_u32 v206, s100, v153, v157
	ds_read_b128 v[202:205], v202 offset:32768
	v_add3_u32 v210, s100, v156, v158
	ds_read_b128 v[206:209], v206 offset:32768
	ds_read_b128 v[210:213], v210 offset:32768
	s_waitcnt lgkmcnt(6)
	s_add_i32 m0, s37, 0x8000
	v_lshl_add_u64 v[228:229], v[226:227], 0, s[28:29]
	v_mfma_f32_32x32x16_bf16 v[114:129], v[166:169], v[174:177], v[114:129]
	global_load_lds_dwordx4 v[228:229], off
	s_add_i32 m0, s37, 0xa000
	v_lshl_add_u64 v[228:229], v[226:227], 0, s[24:25]
	v_mfma_f32_32x32x16_bf16 v[98:113], v[166:169], v[178:181], v[98:113]
	v_mfma_f32_32x32x16_bf16 v[82:97], v[166:169], v[182:185], v[82:97]
	global_load_lds_dwordx4 v[228:229], off
	s_add_i32 m0, s37, 0xc000
	v_lshl_add_u64 v[228:229], v[226:227], 0, s[26:27]
	v_mfma_f32_32x32x16_bf16 v[66:81], v[166:169], v[186:189], v[66:81]
	v_mfma_f32_32x32x16_bf16 v[50:65], v[170:173], v[174:177], v[50:65]
	global_load_lds_dwordx4 v[228:229], off
	s_add_i32 m0, s37, 0xe000
	v_lshl_add_u64 v[228:229], v[226:227], 0, s[38:39]
	v_mfma_f32_32x32x16_bf16 v[34:49], v[170:173], v[178:181], v[34:49]
	v_mfma_f32_32x32x16_bf16 v[18:33], v[170:173], v[182:185], v[18:33]
	global_load_lds_dwordx4 v[228:229], off
	v_mfma_f32_32x32x16_bf16 v[2:17], v[170:173], v[186:189], v[2:17]
	v_add3_u32 v166, s100, v140, v149
	v_add3_u32 v170, s100, v142, v150
	ds_read_b128 v[166:169], v166
	v_add3_u32 v174, s100, v143, v147
	ds_read_b128 v[170:173], v170
	v_add3_u32 v178, s100, v152, v148
	ds_read_b128 v[174:177], v174 offset:32768
	v_add3_u32 v182, s100, v153, v145
	ds_read_b128 v[178:181], v178 offset:32768
	v_add3_u32 v186, s100, v156, v146
	ds_read_b128 v[182:185], v182 offset:32768
	ds_read_b128 v[186:189], v186 offset:32768
	s_waitcnt lgkmcnt(6)
	v_mfma_f32_32x32x16_bf16 v[114:129], v[190:193], v[198:201], v[114:129]
	v_mfma_f32_32x32x16_bf16 v[98:113], v[190:193], v[202:205], v[98:113]
	v_mfma_f32_32x32x16_bf16 v[82:97], v[190:193], v[206:209], v[82:97]
	v_mfma_f32_32x32x16_bf16 v[66:81], v[190:193], v[210:213], v[66:81]
	v_mfma_f32_32x32x16_bf16 v[50:65], v[194:197], v[198:201], v[50:65]
	v_mfma_f32_32x32x16_bf16 v[34:49], v[194:197], v[202:205], v[34:49]
	v_mfma_f32_32x32x16_bf16 v[18:33], v[194:197], v[206:209], v[18:33]
	v_mfma_f32_32x32x16_bf16 v[2:17], v[194:197], v[210:213], v[2:17]
	v_add3_u32 v190, s100, v140, v138
	v_add3_u32 v194, s100, v142, v139
	ds_read_b128 v[190:193], v190
	v_add3_u32 v198, s100, v143, v136
	ds_read_b128 v[194:197], v194
	v_add3_u32 v202, s100, v152, v137
	ds_read_b128 v[198:201], v198 offset:32768
	v_add3_u32 v206, s100, v153, v134
	ds_read_b128 v[202:205], v202 offset:32768
	v_add3_u32 v210, s100, v156, v135
	ds_read_b128 v[206:209], v206 offset:32768
	ds_read_b128 v[210:213], v210 offset:32768
	s_waitcnt lgkmcnt(6)
	v_mfma_f32_32x32x16_bf16 v[114:129], v[166:169], v[174:177], v[114:129]
	v_mfma_f32_32x32x16_bf16 v[98:113], v[166:169], v[178:181], v[98:113]
	v_mfma_f32_32x32x16_bf16 v[82:97], v[166:169], v[182:185], v[82:97]
	v_mfma_f32_32x32x16_bf16 v[66:81], v[166:169], v[186:189], v[66:81]
	v_mfma_f32_32x32x16_bf16 v[50:65], v[170:173], v[174:177], v[50:65]
	v_mfma_f32_32x32x16_bf16 v[34:49], v[170:173], v[178:181], v[34:49]
	v_mfma_f32_32x32x16_bf16 v[18:33], v[170:173], v[182:185], v[18:33]
	v_mfma_f32_32x32x16_bf16 v[2:17], v[170:173], v[186:189], v[2:17]
	s_add_u32 s30, s30, 0x80
	s_addc_u32 s31, s31, 0
	s_add_i32 s7, s7, 0x10000
	s_waitcnt vmcnt(0) lgkmcnt(0)
	s_barrier
	v_add3_u32 v166, s42, v140, v141
	v_add3_u32 v170, s42, v142, v144
	ds_read_b128 v[166:169], v166
	v_add3_u32 v174, s42, v143, v151
	ds_read_b128 v[170:173], v170
	v_add3_u32 v178, s42, v152, v154
	ds_read_b128 v[174:177], v174 offset:32768
	v_add3_u32 v182, s42, v153, v155
	ds_read_b128 v[178:181], v178 offset:32768
	v_add3_u32 v186, s42, v156, v164
	ds_read_b128 v[182:185], v182 offset:32768
	ds_read_b128 v[186:189], v186 offset:32768
	s_cmpk_eq_i32 s30, 0x780
	s_cbranch_scc1 .Lk382_exit
	s_add_i32 s37, s100, s3
	v_lshl_add_u64 v[214:215], v[130:131], 0, s[30:31]
	v_lshl_add_u64 v[226:227], v[132:133], 0, s[30:31]
	s_mov_b32 m0, s37
	v_lshl_add_u64 v[228:229], v[214:215], 0, s[28:29]
	v_mfma_f32_32x32x16_bf16 v[114:129], v[190:193], v[198:201], v[114:129]
	global_load_lds_dwordx4 v[228:229], off
	s_add_i32 m0, s37, 0x2000
	v_lshl_add_u64 v[228:229], v[214:215], 0, s[24:25]
	v_mfma_f32_32x32x16_bf16 v[98:113], v[190:193], v[202:205], v[98:113]
	v_mfma_f32_32x32x16_bf16 v[82:97], v[190:193], v[206:209], v[82:97]
	global_load_lds_dwordx4 v[228:229], off
	s_add_i32 m0, s37, 0x4000
	v_lshl_add_u64 v[228:229], v[214:215], 0, s[26:27]
	v_mfma_f32_32x32x16_bf16 v[66:81], v[190:193], v[210:213], v[66:81]
	v_mfma_f32_32x32x16_bf16 v[50:65], v[194:197], v[198:201], v[50:65]
	global_load_lds_dwordx4 v[228:229], off
	s_add_i32 m0, s37, 0x6000
	v_lshl_add_u64 v[228:229], v[214:215], 0, s[38:39]
	v_mfma_f32_32x32x16_bf16 v[34:49], v[194:197], v[202:205], v[34:49]
	v_mfma_f32_32x32x16_bf16 v[18:33], v[194:197], v[206:209], v[18:33]
	global_load_lds_dwordx4 v[228:229], off
	v_mfma_f32_32x32x16_bf16 v[2:17], v[194:197], v[210:213], v[2:17]
	s_branch .LBB0_382

; DI f32x16 mfma(bf16x8 a, bf16x8 b, f32x16 c) { return __builtin_amdgcn_mfma_f32_32x32x16_bf16(a, b, c, 0, 0, 0); }
;     ...
;   for (int kt = 0; kt < nk; ++kt) {
;     char* cur = lds + (kt & 1) * STG; char* nxt = lds + ((kt + 1) & 1) * STG;
;     const bool more = kt + 1 < nk;
;     const bf16_t* An = Ag + (kt + 1) * BK; const bf16_t* Bn = Bg + (kt + 1) * BK;
;     if (!more) epi.pre(row0 + wm * 64, col0 + wn * (32 * NTW), lane, w, lds);
;     bf16x8 fa[2][2], fb[2][NTW];
; #pragma unroll
;     for (int mt = 0; mt < 2; ++mt) { int row = wm * 64 + mt * 32 + l31; fa[0][mt] = *(const bf16x8*)(cur + row * (BK * 2) + ((hh ^ swz<BK>(row)) << 4)); }
; #pragma unroll
;     for (int nt = 0; nt < NTW; ++nt) { int row = wn * (32 * NTW) + nt * 32 + l31; fb[0][nt] = *(const bf16x8*)(cur + ABYTES + row * (BK * 2) + ((hh ^ swz<BK>(row)) << 4)); }
; #pragma unroll
;     for (int kk = 0; kk < NKK; ++kk) {
;       if (kk + 1 < NKK) {
;         const int ch = (kk + 1) * 2 + hh;
; #pragma unroll
;         for (int mt = 0; mt < 2; ++mt) { int row = wm * 64 + mt * 32 + l31; fa[(kk + 1) & 1][mt] = *(const bf16x8*)(cur + row * (BK * 2) + ((ch ^ swz<BK>(row)) << 4)); }
; #pragma unroll
;         for (int nt = 0; nt < NTW; ++nt) { int row = wn * (32 * NTW) + nt * 32 + l31; fb[(kk + 1) & 1][nt] = *(const bf16x8*)(cur + ABYTES + row * (BK * 2) + ((ch ^ swz<BK>(row)) << 4)); }
;       }
;       if (more) {
; #pragma unroll
;         for (int q = 0; q < PPK; ++q) {
;           const int pi = kk * PPK + q;
;           if (pi < NPA) stage_piece<BM, BK>(An, lda, nxt, tid, pi, wv);
;           else if (pi < NP) stage_piece<BN, BK>(Bn, ldb, nxt + ABYTES, tid, pi - NPA, wv);
;         }
;       }
;       __builtin_amdgcn_s_setprio(1);
; #pragma unroll
;       for (int mt = 0; mt < 2; ++mt)
; #pragma unroll
;         for (int nt = 0; nt < NTW; ++nt) acc[mt][nt] = mfma(fa[kk & 1][mt], fb[kk & 1][nt], acc[mt][nt]);
;       __builtin_amdgcn_s_setprio(0);
;       __builtin_amdgcn_sched_barrier(0);
;     }
;     wait_vm0();
;     __syncthreads();
; __global__ void __launch_bounds__(NT) fwd_megakernel(Params p) {
;     ...
;             for (int t = vb; t < 256; t += gridDim.x) {
;               const int x = t & 7, L = t >> 3; const int pm = 8 * x + (L & 7), pnh = L >> 3;
;               gemm_tile<4, 64, EpiSwiglu, 2>(p.Xb, D_, p.win[i * 2 + f], D_, D_, pm * 256, 5120 + pnh * 128, lds, e1);
;             }
.LBB0_388:
	s_bitcmp1_b32 s3, 0
	s_cselect_b32 s100, 0, 0xc000
	s_cselect_b32 s42, 0xc000, 0
	v_add3_u32 v106, s100, v70, v87
	v_add3_u32 v110, s100, v71, v88
	ds_read_b128 v[106:109], v106
	v_add3_u32 v114, s100, v77, v85
	ds_read_b128 v[110:113], v110
	v_add3_u32 v118, s100, v84, v86
	ds_read_b128 v[114:117], v114 offset:32768
	ds_read_b128 v[118:121], v118 offset:32768
	s_waitcnt lgkmcnt(4)
	s_add_i32 m0, s37, 0x6000
	v_lshl_add_u64 v[126:127], v[122:123], 0, s[38:39]
	v_mfma_f32_32x32x16_bf16 v[50:65], v[90:93], v[98:101], v[50:65]
	global_load_lds_dwordx4 v[126:127], off
	s_add_i32 m0, s37, 0x8000
	v_lshl_add_u64 v[126:127], v[124:125], 0, s[28:29]
	v_mfma_f32_32x32x16_bf16 v[34:49], v[90:93], v[102:105], v[34:49]
	global_load_lds_dwordx4 v[126:127], off
	s_add_i32 m0, s37, 0xa000
	v_lshl_add_u64 v[126:127], v[124:125], 0, s[24:25]
	v_mfma_f32_32x32x16_bf16 v[18:33], v[94:97], v[98:101], v[18:33]
	global_load_lds_dwordx4 v[126:127], off
	v_mfma_f32_32x32x16_bf16 v[2:17], v[94:97], v[102:105], v[2:17]
	v_add3_u32 v90, s100, v70, v81
	v_add3_u32 v94, s100, v71, v82
	ds_read_b128 v[90:93], v90
	v_add3_u32 v98, s100, v77, v78
	ds_read_b128 v[94:97], v94
	v_add3_u32 v102, s100, v84, v79
	ds_read_b128 v[98:101], v98 offset:32768
	ds_read_b128 v[102:105], v102 offset:32768
	s_waitcnt lgkmcnt(4)
	v_mfma_f32_32x32x16_bf16 v[50:65], v[106:109], v[114:117], v[50:65]
	v_mfma_f32_32x32x16_bf16 v[34:49], v[106:109], v[118:121], v[34:49]
	v_mfma_f32_32x32x16_bf16 v[18:33], v[110:113], v[114:117], v[18:33]
	v_mfma_f32_32x32x16_bf16 v[2:17], v[110:113], v[118:121], v[2:17]
	v_add3_u32 v106, s100, v70, v74
	v_add3_u32 v110, s100, v71, v75
	ds_read_b128 v[106:109], v106
	v_add3_u32 v114, s100, v77, v72
	ds_read_b128 v[110:113], v110
	v_add3_u32 v118, s100, v84, v73
	ds_read_b128 v[114:117], v114 offset:32768
	ds_read_b128 v[118:121], v118 offset:32768
	s_waitcnt lgkmcnt(4)
	v_mfma_f32_32x32x16_bf16 v[50:65], v[90:93], v[98:101], v[50:65]
	v_mfma_f32_32x32x16_bf16 v[34:49], v[90:93], v[102:105], v[34:49]
	v_mfma_f32_32x32x16_bf16 v[18:33], v[94:97], v[98:101], v[18:33]
	v_mfma_f32_32x32x16_bf16 v[2:17], v[94:97], v[102:105], v[2:17]
	s_add_u32 s30, s30, 0x80
	s_addc_u32 s31, s31, 0
	s_add_i32 s3, s3, 1
	s_waitcnt vmcnt(0) lgkmcnt(0)
	s_barrier
	v_add3_u32 v90, s42, v70, v76
	v_add3_u32 v94, s42, v71, v80
	ds_read_b128 v[90:93], v90
	v_add3_u32 v98, s42, v77, v83
	ds_read_b128 v[94:97], v94
	v_add3_u32 v102, s42, v84, v89
	ds_read_b128 v[98:101], v98 offset:32768
	ds_read_b128 v[102:105], v102 offset:32768
	s_cmpk_lg_i32 s30, 0x780
	s_cbranch_scc0 .Lk388_exit
	s_add_i32 s37, s7, s100
	v_lshl_add_u64 v[122:123], v[66:67], 0, s[30:31]
	v_lshl_add_u64 v[124:125], v[68:69], 0, s[30:31]
	s_mov_b32 m0, s37
	v_lshl_add_u64 v[126:127], v[122:123], 0, s[28:29]
	v_mfma_f32_32x32x16_bf16 v[50:65], v[106:109], v[114:117], v[50:65]
	global_load_lds_dwordx4 v[126:127], off
	s_add_i32 m0, s37, 0x2000
	v_lshl_add_u64 v[126:127], v[122:123], 0, s[24:25]
	v_mfma_f32_32x32x16_bf16 v[34:49], v[106:109], v[118:121], v[34:49]
	global_load_lds_dwordx4 v[126:127], off
	s_add_i32 m0, s37, 0x4000
	v_lshl_add_u64 v[126:127], v[122:123], 0, s[26:27]
	v_mfma_f32_32x32x16_bf16 v[18:33], v[110:113], v[114:117], v[18:33]
	global_load_lds_dwordx4 v[126:127], off
	v_mfma_f32_32x32x16_bf16 v[2:17], v[110:113], v[118:121], v[2:17]
	s_branch .LBB0_388

; DI f32x16 mfma(bf16x8 a, bf16x8 b, f32x16 c) { return __builtin_amdgcn_mfma_f32_32x32x16_bf16(a, b, c, 0, 0, 0); }
; template <int BK> DI int swz(int row) { constexpr int CPR = BK / 8; return (row / (16 / CPR)) % CPR; }
; DI void wait_vm0() { asm volatile("s_waitcnt vmcnt(0)" ::: "memory"); }
;   DI void pre(int grow0, int gcol0, int lane, int w, char* lds) { xpass(0, grow0, gcol0, lane, w, lds); }
;     ...
;   for (int kt = 0; kt < nk; ++kt) {
;     char* cur = lds + (kt & 1) * STG; char* nxt = lds + ((kt + 1) & 1) * STG;
;     const bool more = kt + 1 < nk;
;     const bf16_t* An = Ag + (kt + 1) * BK; const bf16_t* Bn = Bg + (kt + 1) * BK;
;     if (!more) epi.pre(row0 + wm * 64, col0 + wn * (32 * NTW), lane, w, lds);
;     bf16x8 fa[2][2], fb[2][NTW];
; #pragma unroll
;     for (int mt = 0; mt < 2; ++mt) { int row = wm * 64 + mt * 32 + l31; fa[0][mt] = *(const bf16x8*)(cur + row * (BK * 2) + ((hh ^ swz<BK>(row)) << 4)); }
; #pragma unroll
;     for (int nt = 0; nt < NTW; ++nt) { int row = wn * (32 * NTW) + nt * 32 + l31; fb[0][nt] = *(const bf16x8*)(cur + ABYTES + row * (BK * 2) + ((hh ^ swz<BK>(row)) << 4)); }
; #pragma unroll
;     for (int kk = 0; kk < NKK; ++kk) {
;       if (kk + 1 < NKK) {
;         const int ch = (kk + 1) * 2 + hh;
; #pragma unroll
;         for (int mt = 0; mt < 2; ++mt) { int row = wm * 64 + mt * 32 + l31; fa[(kk + 1) & 1][mt] = *(const bf16x8*)(cur + row * (BK * 2) + ((ch ^ swz<BK>(row)) << 4)); }
; #pragma unroll
;         for (int nt = 0; nt < NTW; ++nt) { int row = wn * (32 * NTW) + nt * 32 + l31; fb[(kk + 1) & 1][nt] = *(const bf16x8*)(cur + ABYTES + row * (BK * 2) + ((ch ^ swz<BK>(row)) << 4)); }
;       }
;       if (more) {
; #pragma unroll
;         for (int q = 0; q < PPK; ++q) {
;           const int pi = kk * PPK + q;
;           if (pi < NPA) stage_piece<BM, BK>(An, lda, nxt, tid, pi, wv);
;           else if (pi < NP) stage_piece<BN, BK>(Bn, ldb, nxt + ABYTES, tid, pi - NPA, wv);
;         }
;       }
;       __builtin_amdgcn_s_setprio(1);
; #pragma unroll
;       for (int mt = 0; mt < 2; ++mt)
; #pragma unroll
;         for (int nt = 0; nt < NTW; ++nt) acc[mt][nt] = mfma(fa[kk & 1][mt], fb[kk & 1][nt], acc[mt][nt]);
;       __builtin_amdgcn_s_setprio(0);
;       __builtin_amdgcn_sched_barrier(0);
;     }
;     wait_vm0();
;     __syncthreads();
.LBB0_439:
	s_and_b32 s40, s7, 0x10000
	s_xor_b32 s100, s40, 0x10000
	v_add3_u32 v190, s100, v140, v161
	v_add3_u32 v194, s100, v142, v163
	ds_read_b128 v[190:193], v190
	v_add3_u32 v198, s100, v143, v159
	ds_read_b128 v[194:197], v194
	v_add3_u32 v202, s100, v152, v160
	ds_read_b128 v[198:201], v198 offset:32768
	v_add3_u32 v206, s100, v153, v157
	ds_read_b128 v[202:205], v202 offset:32768
	v_add3_u32 v210, s100, v156, v158
	ds_read_b128 v[206:209], v206 offset:32768
	ds_read_b128 v[210:213], v210 offset:32768
	s_waitcnt lgkmcnt(6)
	s_add_i32 m0, s37, 0x8000
	v_lshl_add_u64 v[228:229], v[226:227], 0, s[28:29]
	v_mfma_f32_32x32x16_bf16 v[114:129], v[166:169], v[174:177], v[114:129]
	global_load_lds_dwordx4 v[228:229], off
	s_add_i32 m0, s37, 0xa000
	v_lshl_add_u64 v[228:229], v[226:227], 0, s[24:25]
	v_mfma_f32_32x32x16_bf16 v[98:113], v[166:169], v[178:181], v[98:113]
	v_mfma_f32_32x32x16_bf16 v[50:65], v[166:169], v[182:185], v[50:65]
	global_load_lds_dwordx4 v[228:229], off
	s_add_i32 m0, s37, 0xc000
	v_lshl_add_u64 v[228:229], v[226:227], 0, s[26:27]
	v_mfma_f32_32x32x16_bf16 v[34:49], v[166:169], v[186:189], v[34:49]
	v_mfma_f32_32x32x16_bf16 v[82:97], v[170:173], v[174:177], v[82:97]
	global_load_lds_dwordx4 v[228:229], off
	s_add_i32 m0, s37, 0xe000
	v_lshl_add_u64 v[228:229], v[226:227], 0, s[38:39]
	v_mfma_f32_32x32x16_bf16 v[66:81], v[170:173], v[178:181], v[66:81]
	v_mfma_f32_32x32x16_bf16 v[18:33], v[170:173], v[182:185], v[18:33]
	global_load_lds_dwordx4 v[228:229], off
	v_mfma_f32_32x32x16_bf16 v[2:17], v[170:173], v[186:189], v[2:17]
	v_add3_u32 v166, s100, v140, v149
	v_add3_u32 v170, s100, v142, v150
	ds_read_b128 v[166:169], v166
	v_add3_u32 v174, s100, v143, v147
	ds_read_b128 v[170:173], v170
	v_add3_u32 v178, s100, v152, v148
	ds_read_b128 v[174:177], v174 offset:32768
	v_add3_u32 v182, s100, v153, v145
	ds_read_b128 v[178:181], v178 offset:32768
	v_add3_u32 v186, s100, v156, v146
	ds_read_b128 v[182:185], v182 offset:32768
	ds_read_b128 v[186:189], v186 offset:32768
	s_waitcnt lgkmcnt(6)
	v_mfma_f32_32x32x16_bf16 v[114:129], v[190:193], v[198:201], v[114:129]
	v_mfma_f32_32x32x16_bf16 v[98:113], v[190:193], v[202:205], v[98:113]
	v_mfma_f32_32x32x16_bf16 v[50:65], v[190:193], v[206:209], v[50:65]
	v_mfma_f32_32x32x16_bf16 v[34:49], v[190:193], v[210:213], v[34:49]
	v_mfma_f32_32x32x16_bf16 v[82:97], v[194:197], v[198:201], v[82:97]
	v_mfma_f32_32x32x16_bf16 v[66:81], v[194:197], v[202:205], v[66:81]
	v_mfma_f32_32x32x16_bf16 v[18:33], v[194:197], v[206:209], v[18:33]
	v_mfma_f32_32x32x16_bf16 v[2:17], v[194:197], v[210:213], v[2:17]
	v_add3_u32 v190, s100, v140, v138
	v_add3_u32 v194, s100, v142, v139
	ds_read_b128 v[190:193], v190
	v_add3_u32 v198, s100, v143, v136
	ds_read_b128 v[194:197], v194
	v_add3_u32 v202, s100, v152, v137
	ds_read_b128 v[198:201], v198 offset:32768
	v_add3_u32 v206, s100, v153, v134
	ds_read_b128 v[202:205], v202 offset:32768
	v_add3_u32 v210, s100, v156, v135
	ds_read_b128 v[206:209], v206 offset:32768
	ds_read_b128 v[210:213], v210 offset:32768
	s_waitcnt lgkmcnt(6)
	v_mfma_f32_32x32x16_bf16 v[114:129], v[166:169], v[174:177], v[114:129]
	v_mfma_f32_32x32x16_bf16 v[98:113], v[166:169], v[178:181], v[98:113]
	v_mfma_f32_32x32x16_bf16 v[50:65], v[166:169], v[182:185], v[50:65]
	v_mfma_f32_32x32x16_bf16 v[34:49], v[166:169], v[186:189], v[34:49]
	v_mfma_f32_32x32x16_bf16 v[82:97], v[170:173], v[174:177], v[82:97]
	v_mfma_f32_32x32x16_bf16 v[66:81], v[170:173], v[178:181], v[66:81]
	v_mfma_f32_32x32x16_bf16 v[18:33], v[170:173], v[182:185], v[18:33]
	v_mfma_f32_32x32x16_bf16 v[2:17], v[170:173], v[186:189], v[2:17]
	s_add_u32 s30, s30, 0x80
	s_addc_u32 s31, s31, 0
	s_add_i32 s7, s7, 0x10000
	s_waitcnt vmcnt(0) lgkmcnt(0)
	s_barrier
	v_add3_u32 v166, s40, v140, v141
	v_add3_u32 v170, s40, v142, v144
	ds_read_b128 v[166:169], v166
	v_add3_u32 v174, s40, v143, v151
	ds_read_b128 v[170:173], v170
	v_add3_u32 v178, s40, v152, v154
	ds_read_b128 v[174:177], v174 offset:32768
	v_add3_u32 v182, s40, v153, v155
	ds_read_b128 v[178:181], v178 offset:32768
	v_add3_u32 v186, s40, v156, v164
	ds_read_b128 v[182:185], v182 offset:32768
	ds_read_b128 v[186:189], v186 offset:32768
	s_cmpk_eq_i32 s30, 0x780
	s_cbranch_scc1 .Lk439_exit
	s_add_i32 s37, s100, s3
	v_lshl_add_u64 v[214:215], v[130:131], 0, s[30:31]
	v_lshl_add_u64 v[226:227], v[132:133], 0, s[30:31]
	s_mov_b32 m0, s37
	v_lshl_add_u64 v[228:229], v[214:215], 0, s[28:29]
	v_mfma_f32_32x32x16_bf16 v[114:129], v[190:193], v[198:201], v[114:129]
	global_load_lds_dwordx4 v[228:229], off
	s_add_i32 m0, s37, 0x2000
	v_lshl_add_u64 v[228:229], v[214:215], 0, s[24:25]
	v_mfma_f32_32x32x16_bf16 v[98:113], v[190:193], v[202:205], v[98:113]
	v_mfma_f32_32x32x16_bf16 v[50:65], v[190:193], v[206:209], v[50:65]
	global_load_lds_dwordx4 v[228:229], off
	s_add_i32 m0, s37, 0x4000
	v_lshl_add_u64 v[228:229], v[214:215], 0, s[26:27]
	v_mfma_f32_32x32x16_bf16 v[34:49], v[190:193], v[210:213], v[34:49]
	v_mfma_f32_32x32x16_bf16 v[82:97], v[194:197], v[198:201], v[82:97]
	global_load_lds_dwordx4 v[228:229], off
	s_add_i32 m0, s37, 0x6000
	v_lshl_add_u64 v[228:229], v[214:215], 0, s[38:39]
	v_mfma_f32_32x32x16_bf16 v[66:81], v[194:197], v[202:205], v[66:81]
	v_mfma_f32_32x32x16_bf16 v[18:33], v[194:197], v[206:209], v[18:33]
	global_load_lds_dwordx4 v[228:229], off
	v_mfma_f32_32x32x16_bf16 v[2:17], v[194:197], v[210:213], v[2:17]
	s_branch .LBB0_439

; DI f32x16 zero16() { f32x16 z; for (int i = 0; i < 16; ++i) z[i] = 0.f; return z; }
; DI int launder(int x) { asm volatile("" : "+v"(x)); return x; }
; DI void wait_vm0() { asm volatile("s_waitcnt vmcnt(0)" ::: "memory"); }
;   DI void pre(int grow0, int gcol0, int lane, int w, char* lds) { xpass(0, grow0, gcol0, lane, w, lds); }
; template <int BK> DI int swz(int row) { constexpr int CPR = BK / 8; return (row / (16 / CPR)) % CPR; }
; template <int ROWS, int BK>
; DI void stage_tile(const bf16_t* g, int ld, char* l, int tid) {
;   constexpr int CPR = BK / 8, TOT = ROWS * CPR, N = (TOT + NT - 1) / NT;
;   const int row0 = tid / CPR, pc = tid % CPR; const int c = pc ^ swz<BK>(row0);
;   const unsigned voff = (unsigned)(row0 * ld + c * 8) * 2u;
; #pragma unroll
;   for (int i = 0; i < N; ++i) {
;     if (TOT % NT == 0 || tid + i * NT < TOT) {
;       const char* gb = (const char*)g + (size_t)i * (NT / CPR) * ld * 2;
;       __builtin_amdgcn_global_load_lds((const unsigned*)(gb + voff), (__attribute__((address_space(3))) unsigned*)(l + i * NT * 16 + __builtin_amdgcn_readfirstlane(tid >> 6) * 1024), 16, 0, 0);
;     }
;   }
; }
;     ...
;   const int tid = launder(threadIdx.x), lane = tid & 63, w = tid >> 6, wm = w % WM, wn = w / WM;
;   const int l31 = lane & 31, hh = lane >> 5;
;   f32x16 acc[2][NTW];
; #pragma unroll
;   for (int a = 0; a < 2; ++a)
; #pragma unroll
;     for (int b = 0; b < NTW; ++b) acc[a][b] = zero16();
;   const bf16_t* Ag = A + (size_t)row0 * lda; const bf16_t* Bg = Bt + (size_t)col0 * ldb;
;   const int wv = __builtin_amdgcn_readfirstlane(tid >> 6);
;   __syncthreads();
;   if (!pre) { stage_tile<BM, BK>(Ag, lda, lds, tid); stage_tile<BN, BK>(Bg, ldb, lds + ABYTES, tid); }
;   wait_vm0();
;   __syncthreads();
.LBB0_530:
	v_readlane_b32 s2, v255, 17
	v_readlane_b32 s3, v255, 18
	s_mov_b64 s[6:7], -1
	s_and_b64 vcc, exec, s[2:3]
	s_cbranch_vccz .LBB0_615
	s_waitcnt lgkmcnt(0)
	v_mov_b32_e32 v6, v216
	v_readlane_b32 s2, v255, 46
	v_ashrrev_i32_e32 v2, 31, v6
	v_lshrrev_b32_e32 v3, 29, v2
	v_lshrrev_b32_e32 v2, 28, v2
	v_add_u32_e32 v2, v6, v2
	v_ashrrev_i32_e32 v2, 4, v2
	v_lshrrev_b32_e32 v5, 29, v2
	v_add_u32_e32 v3, v6, v3
	v_add_u32_e32 v5, v2, v5
	v_ashrrev_i32_e32 v4, 3, v3
	v_and_b32_e32 v3, 0xffffff8, v3
	v_and_b32_e32 v5, 0xffffff8, v5
	v_sub_u32_e32 v3, v6, v3
	v_sub_u32_e32 v2, v2, v5
	v_readlane_b32 s7, v255, 26
	v_readlane_b32 s3, v255, 47
	s_add_u32 s2, s42, s2
	v_xor_b32_e32 v2, v2, v3
	v_lshlrev_b32_e32 v3, s7, v4
	v_readfirstlane_b32 s7, v6
	s_addc_u32 s3, s43, s3
	v_readlane_b32 s30, v255, 27
	s_lshl_b32 s7, s7, 4
	v_lshl_add_u32 v2, v2, 4, v3
	v_mov_b32_e32 v3, v1
	v_readlane_b32 s31, v255, 28
	s_and_b32 s7, s7, 0xfffffc00
	v_readlane_b32 s36, v255, 41
	s_waitcnt vmcnt(0)
	v_lshl_add_u64 v[130:131], s[30:31], 0, v[2:3]
	s_mov_b32 m0, s7
	v_readlane_b32 s37, v255, 42
	v_readlane_b32 s40, v255, 43
	s_barrier
	global_load_lds_dwordx4 v2, s[30:31]
	v_lshl_add_u64 v[4:5], v[130:131], 0, s[36:37]
	s_add_i32 m0, s7, 0x2000
	v_readlane_b32 s41, v255, 44
	v_readlane_b32 s34, v255, 48
	global_load_lds_dwordx4 v[4:5], off
	v_lshl_add_u64 v[4:5], v[130:131], 0, s[40:41]
	s_add_i32 m0, s7, 0x4000
	v_readlane_b32 s35, v255, 49
	global_load_lds_dwordx4 v[4:5], off
	s_nop 0
	v_lshl_add_u64 v[4:5], v[130:131], 0, s[34:35]
	s_add_i32 m0, s7, 0x6000
	v_lshl_add_u64 v[132:133], s[2:3], 0, v[2:3]
	global_load_lds_dwordx4 v[4:5], off
	s_add_i32 m0, s7, 0x8000
	v_ashrrev_i32_e32 v134, 6, v6
	global_load_lds_dwordx4 v2, s[2:3]
	v_lshl_add_u64 v[2:3], v[132:133], 0, s[36:37]
	s_add_i32 m0, s7, 0xa000
	v_and_b32_e32 v4, 31, v6
	global_load_lds_dwordx4 v[2:3], off
	v_lshl_add_u64 v[2:3], v[132:133], 0, s[40:41]
	s_add_i32 m0, s7, 0xc000
	v_and_b32_e32 v0, 63, v6
	global_load_lds_dwordx4 v[2:3], off
	v_lshl_add_u64 v[2:3], v[132:133], 0, s[34:35]
	s_add_i32 m0, s7, 0xe000
	v_bfe_u32 v135, v6, 5, 1
	global_load_lds_dwordx4 v[2:3], off
	v_lshrrev_b32_e32 v2, 30, v134
	v_add_u32_e32 v2, v134, v2
	v_ashrrev_i32_e32 v3, 2, v2
	v_mul_i32_i24_e32 v5, 4, v3
	v_sub_u32_e32 v5, v134, v5
	v_lshlrev_b32_e32 v169, 6, v5
	v_lshlrev_b32_e32 v161, 7, v3
	v_or_b32_e32 v3, v169, v4
	v_bfe_u32 v5, v5, 25, 1
	v_lshlrev_b32_e32 v136, 7, v3
	v_add_u32_e32 v6, v3, v5
	v_or_b32_e32 v3, 32, v3
	v_lshlrev_b32_e32 v144, 7, v3
	v_add_u32_e32 v3, v3, v5
	v_ashrrev_i32_e32 v5, 1, v3
	v_ashrrev_i32_e32 v3, 31, v3
	v_ashrrev_i32_e32 v7, 1, v6
	v_ashrrev_i32_e32 v6, 31, v6
	v_lshrrev_b32_e32 v3, 29, v3
	v_lshrrev_b32_e32 v6, 29, v6
	v_add_u32_e32 v3, v5, v3
	v_add_u32_e32 v6, v7, v6
	v_and_b32_e32 v3, -8, v3
	v_and_b32_e32 v6, -8, v6
	v_sub_u32_e32 v3, v5, v3
	v_or_b32_e32 v4, v161, v4
	v_sub_u32_e32 v6, v7, v6
	v_xor_b32_e32 v5, v3, v135
	v_lshrrev_b32_e32 v2, 31, v2
	v_xor_b32_e32 v7, v6, v135
	v_lshlrev_b32_e32 v146, 4, v5
	v_add_u32_e32 v5, v4, v2
	v_lshlrev_b32_e32 v143, 4, v7
	v_ashrrev_i32_e32 v7, 1, v5
	v_ashrrev_i32_e32 v5, 31, v5
	v_lshrrev_b32_e32 v5, 29, v5
	v_add_u32_e32 v5, v7, v5
	v_and_b32_e32 v5, -8, v5
	v_sub_u32_e32 v5, v7, v5
	v_xor_b32_e32 v7, v5, v135
	v_lshlrev_b32_e32 v149, 4, v7
	v_or_b32_e32 v7, 32, v4
	v_lshlrev_b32_e32 v150, 7, v7
	v_add_u32_e32 v7, v7, v2
	v_ashrrev_i32_e32 v8, 1, v7
	v_ashrrev_i32_e32 v7, 31, v7
	v_lshrrev_b32_e32 v7, 29, v7
	v_add_u32_e32 v7, v8, v7
	v_and_b32_e32 v7, -8, v7
	v_sub_u32_e32 v7, v8, v7
	v_xor_b32_e32 v8, v7, v135
	v_lshlrev_b32_e32 v145, 7, v4
	v_lshlrev_b32_e32 v155, 4, v8
	v_or_b32_e32 v8, 64, v4
	v_or_b32_e32 v4, 0x60, v4
	v_lshlrev_b32_e32 v156, 7, v8
	v_add_u32_e32 v8, v8, v2
	v_add_u32_e32 v2, v4, v2
	v_lshlrev_b32_e32 v158, 7, v4
	v_ashrrev_i32_e32 v4, 1, v2
	v_ashrrev_i32_e32 v2, 31, v2
	v_lshrrev_b32_e32 v2, 29, v2
	v_add_u32_e32 v2, v4, v2
	v_and_b32_e32 v2, -8, v2
	v_sub_u32_e32 v2, v4, v2
	v_ashrrev_i32_e32 v9, 1, v8
	v_ashrrev_i32_e32 v8, 31, v8
	v_xor_b32_e32 v4, v2, v135
	v_lshrrev_b32_e32 v8, 29, v8
	v_lshlrev_b32_e32 v168, 4, v4
	v_bitop3_b32 v4, v6, v135, 2 bitop3:0x1e
	v_add_u32_e32 v8, v9, v8
	v_lshlrev_b32_e32 v166, 4, v4
	v_bitop3_b32 v4, v3, v135, 2 bitop3:0x1e
	v_and_b32_e32 v8, -8, v8
	v_lshlrev_b32_e32 v167, 4, v4
	v_bitop3_b32 v4, v5, v135, 2 bitop3:0x1e
	v_sub_u32_e32 v8, v9, v8
	v_lshlrev_b32_e32 v163, 4, v4
	v_bitop3_b32 v4, v7, v135, 2 bitop3:0x1e
	v_lshlrev_b32_e32 v164, 4, v4
	v_bitop3_b32 v4, v8, v135, 2 bitop3:0x1e
	v_lshlrev_b32_e32 v159, 4, v4
	v_bitop3_b32 v4, v2, v135, 2 bitop3:0x1e
	v_lshlrev_b32_e32 v160, 4, v4
	v_bitop3_b32 v4, v6, v135, 4 bitop3:0x1e
	v_lshlrev_b32_e32 v153, 4, v4
	v_bitop3_b32 v4, v3, v135, 4 bitop3:0x1e
	v_lshlrev_b32_e32 v154, 4, v4
	v_bitop3_b32 v4, v5, v135, 4 bitop3:0x1e
	v_lshlrev_b32_e32 v151, 4, v4
	v_bitop3_b32 v4, v7, v135, 4 bitop3:0x1e
	v_bitop3_b32 v3, v3, v135, 6 bitop3:0x1e
	v_lshlrev_b32_e32 v152, 4, v4
	v_bitop3_b32 v4, v8, v135, 4 bitop3:0x1e
	v_lshlrev_b32_e32 v142, 4, v3
	v_bitop3_b32 v3, v5, v135, 6 bitop3:0x1e
	s_waitcnt vmcnt(0)
; DI f32x16 zero16() { f32x16 z; for (int i = 0; i < 16; ++i) z[i] = 0.f; return z; }
; DI int launder(int x) { asm volatile("" : "+v"(x)); return x; }
; template <int BK> DI int swz(int row) { constexpr int CPR = BK / 8; return (row / (16 / CPR)) % CPR; }
; DI void wait_vm0() { asm volatile("s_waitcnt vmcnt(0)" ::: "memory"); }
;   DI void pre(int grow0, int gcol0, int lane, int w, char* lds) { xpass(0, grow0, gcol0, lane, w, lds); }
;     ...
;   const int tid = launder(threadIdx.x), lane = tid & 63, w = tid >> 6, wm = w % WM, wn = w / WM;
;   const int l31 = lane & 31, hh = lane >> 5;
;   f32x16 acc[2][NTW];
; #pragma unroll
;   for (int a = 0; a < 2; ++a)
; #pragma unroll
;     for (int b = 0; b < NTW; ++b) acc[a][b] = zero16();
;   const bf16_t* Ag = A + (size_t)row0 * lda; const bf16_t* Bg = Bt + (size_t)col0 * ldb;
;   const int wv = __builtin_amdgcn_readfirstlane(tid >> 6);
;   __syncthreads();
;   if (!pre) { stage_tile<BM, BK>(Ag, lda, lds, tid); stage_tile<BN, BK>(Bg, ldb, lds + ABYTES, tid); }
;   wait_vm0();
;   __syncthreads();
;   const int nk = K / BK;
;   for (int kt = 0; kt < nk; ++kt) {
;     char* cur = lds + (kt & 1) * STG; char* nxt = lds + ((kt + 1) & 1) * STG;
;     const bool more = kt + 1 < nk;
;     const bf16_t* An = Ag + (kt + 1) * BK; const bf16_t* Bn = Bg + (kt + 1) * BK;
;     if (!more) epi.pre(row0 + wm * 64, col0 + wn * (32 * NTW), lane, w, lds);
;     bf16x8 fa[2][2], fb[2][NTW];
; #pragma unroll
;     for (int mt = 0; mt < 2; ++mt) { int row = wm * 64 + mt * 32 + l31; fa[0][mt] = *(const bf16x8*)(cur + row * (BK * 2) + ((hh ^ swz<BK>(row)) << 4)); }
; #pragma unroll
;     for (int nt = 0; nt < NTW; ++nt) { int row = wn * (32 * NTW) + nt * 32 + l31; fb[0][nt] = *(const bf16x8*)(cur + ABYTES + row * (BK * 2) + ((hh ^ swz<BK>(row)) << 4)); }
; #pragma unroll
;     for (int kk = 0; kk < NKK; ++kk) {
;       if (kk + 1 < NKK) {
;         const int ch = (kk + 1) * 2 + hh;
; #pragma unroll
;         for (int mt = 0; mt < 2; ++mt) { int row = wm * 64 + mt * 32 + l31; fa[(kk + 1) & 1][mt] = *(const bf16x8*)(cur + row * (BK * 2) + ((ch ^ swz<BK>(row)) << 4)); }
; #pragma unroll
;         for (int nt = 0; nt < NTW; ++nt) { int row = wn * (32 * NTW) + nt * 32 + l31; fb[(kk + 1) & 1][nt] = *(const bf16x8*)(cur + ABYTES + row * (BK * 2) + ((ch ^ swz<BK>(row)) << 4)); }
	v_lshlrev_b32_e32 v147, 4, v4
	v_bitop3_b32 v4, v2, v135, 4 bitop3:0x1e
	v_lshlrev_b32_e32 v139, 4, v3
	v_bitop3_b32 v3, v7, v135, 6 bitop3:0x1e
	v_bitop3_b32 v2, v2, v135, 6 bitop3:0x1e
	v_readfirstlane_b32 s6, v134
	v_xor_b32_e32 v9, v8, v135
	v_lshlrev_b32_e32 v148, 4, v4
	v_bitop3_b32 v4, v6, v135, 6 bitop3:0x1e
	v_lshlrev_b32_e32 v140, 4, v3
	v_bitop3_b32 v3, v8, v135, 6 bitop3:0x1e
	v_lshlrev_b32_e32 v138, 4, v2
	v_mov_b32_e32 v2, 0
	s_lshl_b32 s2, s6, 10
	s_mov_b32 s92, 64
	v_lshlrev_b32_e32 v157, 4, v9
	v_lshlrev_b32_e32 v141, 4, v4
	v_lshlrev_b32_e32 v137, 4, v3
	s_mov_b32 s3, 0x10000
	v_readlane_b32 s6, v255, 45
	v_mov_b32_e32 v3, v2
	v_mov_b32_e32 v4, v2
	v_mov_b32_e32 v5, v2
	v_mov_b32_e32 v6, v2
	v_mov_b32_e32 v7, v2
	v_mov_b32_e32 v8, v2
	v_mov_b32_e32 v9, v2
	v_mov_b32_e32 v10, v2
	v_mov_b32_e32 v11, v2
	v_mov_b32_e32 v12, v2
	v_mov_b32_e32 v13, v2
	v_mov_b32_e32 v14, v2
	v_mov_b32_e32 v15, v2
	v_mov_b32_e32 v16, v2
	v_mov_b32_e32 v17, v2
	v_mov_b32_e32 v18, v2
	v_mov_b32_e32 v19, v2
	v_mov_b32_e32 v20, v2
	v_mov_b32_e32 v21, v2
	v_mov_b32_e32 v22, v2
	v_mov_b32_e32 v23, v2
	v_mov_b32_e32 v24, v2
	v_mov_b32_e32 v25, v2
	v_mov_b32_e32 v26, v2
	v_mov_b32_e32 v27, v2
	v_mov_b32_e32 v28, v2
	v_mov_b32_e32 v29, v2
	v_mov_b32_e32 v30, v2
	v_mov_b32_e32 v31, v2
	v_mov_b32_e32 v32, v2
	v_mov_b32_e32 v33, v2
	v_mov_b32_e32 v34, v2
	v_mov_b32_e32 v35, v2
	v_mov_b32_e32 v36, v2
	v_mov_b32_e32 v37, v2
	v_mov_b32_e32 v38, v2
	v_mov_b32_e32 v39, v2
	v_mov_b32_e32 v40, v2
	v_mov_b32_e32 v41, v2
	v_mov_b32_e32 v42, v2
	v_mov_b32_e32 v43, v2
	v_mov_b32_e32 v44, v2
	v_mov_b32_e32 v45, v2
	v_mov_b32_e32 v46, v2
	v_mov_b32_e32 v47, v2
	v_mov_b32_e32 v48, v2
	v_mov_b32_e32 v49, v2
	v_mov_b32_e32 v50, v2
	v_mov_b32_e32 v51, v2
	v_mov_b32_e32 v52, v2
	v_mov_b32_e32 v53, v2
	v_mov_b32_e32 v54, v2
	v_mov_b32_e32 v55, v2
	v_mov_b32_e32 v56, v2
	v_mov_b32_e32 v57, v2
	v_mov_b32_e32 v58, v2
	v_mov_b32_e32 v59, v2
	v_mov_b32_e32 v60, v2
	v_mov_b32_e32 v61, v2
	v_mov_b32_e32 v62, v2
	v_mov_b32_e32 v63, v2
	v_mov_b32_e32 v64, v2
	v_mov_b32_e32 v65, v2
	v_mov_b32_e32 v66, v2
	v_mov_b32_e32 v67, v2
	v_mov_b32_e32 v68, v2
	v_mov_b32_e32 v69, v2
	v_mov_b32_e32 v70, v2
	v_mov_b32_e32 v71, v2
	v_mov_b32_e32 v72, v2
	v_mov_b32_e32 v73, v2
	v_mov_b32_e32 v74, v2
	v_mov_b32_e32 v75, v2
	v_mov_b32_e32 v76, v2
	v_mov_b32_e32 v77, v2
	v_mov_b32_e32 v78, v2
	v_mov_b32_e32 v79, v2
	v_mov_b32_e32 v80, v2
	v_mov_b32_e32 v81, v2
	v_mov_b32_e32 v82, v2
	v_mov_b32_e32 v83, v2
	v_mov_b32_e32 v84, v2
	v_mov_b32_e32 v85, v2
	v_mov_b32_e32 v86, v2
	v_mov_b32_e32 v87, v2
	v_mov_b32_e32 v88, v2
	v_mov_b32_e32 v89, v2
	v_mov_b32_e32 v90, v2
	v_mov_b32_e32 v91, v2
	v_mov_b32_e32 v92, v2
	v_mov_b32_e32 v93, v2
	v_mov_b32_e32 v94, v2
	v_mov_b32_e32 v95, v2
	v_mov_b32_e32 v96, v2
	v_mov_b32_e32 v97, v2
	v_mov_b32_e32 v98, v2
	v_mov_b32_e32 v99, v2
	v_mov_b32_e32 v100, v2
	v_mov_b32_e32 v101, v2
	v_mov_b32_e32 v102, v2
	v_mov_b32_e32 v103, v2
	v_mov_b32_e32 v104, v2
	v_mov_b32_e32 v105, v2
	v_mov_b32_e32 v106, v2
	v_mov_b32_e32 v107, v2
	v_mov_b32_e32 v108, v2
	v_mov_b32_e32 v109, v2
	v_mov_b32_e32 v110, v2
	v_mov_b32_e32 v111, v2
	v_mov_b32_e32 v112, v2
	v_mov_b32_e32 v113, v2
	v_mov_b32_e32 v114, v2
	v_mov_b32_e32 v115, v2
	v_mov_b32_e32 v116, v2
	v_mov_b32_e32 v117, v2
	v_mov_b32_e32 v118, v2
	v_mov_b32_e32 v119, v2
	v_mov_b32_e32 v120, v2
	v_mov_b32_e32 v121, v2
	v_mov_b32_e32 v122, v2
	v_mov_b32_e32 v123, v2
	v_mov_b32_e32 v124, v2
	v_mov_b32_e32 v125, v2
	v_mov_b32_e32 v126, v2
	v_mov_b32_e32 v127, v2
	v_mov_b32_e32 v128, v2
	v_mov_b32_e32 v129, v2
	s_waitcnt vmcnt(0) lgkmcnt(0)
	s_barrier
	v_add_u32_e32 v170, v136, v143
	v_add_u32_e32 v174, v144, v146
	ds_read_b128 v[170:173], v170
	v_add_u32_e32 v178, v145, v149
	ds_read_b128 v[174:177], v174
	v_add_u32_e32 v182, v150, v155
	ds_read_b128 v[178:181], v178 offset:32768
	v_add_u32_e32 v186, v156, v157
	ds_read_b128 v[182:185], v182 offset:32768
	v_add_u32_e32 v190, v158, v168
	ds_read_b128 v[186:189], v186 offset:32768
	ds_read_b128 v[190:193], v190 offset:32768
	s_and_b32 s7, s3, 0x10000
	s_add_i32 s101, s7, s2
	s_lshl_b64 s[30:31], s[92:93], 1
	v_lshl_add_u64 v[230:231], v[130:131], 0, s[30:31]
	v_lshl_add_u64 v[214:215], v[132:133], 0, s[30:31]
	s_mov_b32 m0, s101
	v_mov_b64_e32 v[232:233], v[230:231]
	global_load_lds_dwordx4 v[232:233], off
	s_add_i32 m0, s101, 0x2000
	v_lshl_add_u64 v[232:233], v[230:231], 0, s[36:37]
	global_load_lds_dwordx4 v[232:233], off
	s_add_i32 m0, s101, 0x4000
	v_lshl_add_u64 v[232:233], v[230:231], 0, s[40:41]
	global_load_lds_dwordx4 v[232:233], off
	s_add_i32 m0, s101, 0x6000
	v_lshl_add_u64 v[232:233], v[230:231], 0, s[34:35]
	global_load_lds_dwordx4 v[232:233], off
; DI f32x16 mfma(bf16x8 a, bf16x8 b, f32x16 c) { return __builtin_amdgcn_mfma_f32_32x32x16_bf16(a, b, c, 0, 0, 0); }
; template <int BK> DI int swz(int row) { constexpr int CPR = BK / 8; return (row / (16 / CPR)) % CPR; }
; DI void wait_vm0() { asm volatile("s_waitcnt vmcnt(0)" ::: "memory"); }
;   DI void pre(int grow0, int gcol0, int lane, int w, char* lds) { xpass(0, grow0, gcol0, lane, w, lds); }
;     ...
;   for (int kt = 0; kt < nk; ++kt) {
;     char* cur = lds + (kt & 1) * STG; char* nxt = lds + ((kt + 1) & 1) * STG;
;     const bool more = kt + 1 < nk;
;     const bf16_t* An = Ag + (kt + 1) * BK; const bf16_t* Bn = Bg + (kt + 1) * BK;
;     if (!more) epi.pre(row0 + wm * 64, col0 + wn * (32 * NTW), lane, w, lds);
;     bf16x8 fa[2][2], fb[2][NTW];
; #pragma unroll
;     for (int mt = 0; mt < 2; ++mt) { int row = wm * 64 + mt * 32 + l31; fa[0][mt] = *(const bf16x8*)(cur + row * (BK * 2) + ((hh ^ swz<BK>(row)) << 4)); }
; #pragma unroll
;     for (int nt = 0; nt < NTW; ++nt) { int row = wn * (32 * NTW) + nt * 32 + l31; fb[0][nt] = *(const bf16x8*)(cur + ABYTES + row * (BK * 2) + ((hh ^ swz<BK>(row)) << 4)); }
; #pragma unroll
;     for (int kk = 0; kk < NKK; ++kk) {
;       if (kk + 1 < NKK) {
;         const int ch = (kk + 1) * 2 + hh;
; #pragma unroll
;         for (int mt = 0; mt < 2; ++mt) { int row = wm * 64 + mt * 32 + l31; fa[(kk + 1) & 1][mt] = *(const bf16x8*)(cur + row * (BK * 2) + ((ch ^ swz<BK>(row)) << 4)); }
; #pragma unroll
;         for (int nt = 0; nt < NTW; ++nt) { int row = wn * (32 * NTW) + nt * 32 + l31; fb[(kk + 1) & 1][nt] = *(const bf16x8*)(cur + ABYTES + row * (BK * 2) + ((ch ^ swz<BK>(row)) << 4)); }
;       }
;       if (more) {
; #pragma unroll
;         for (int q = 0; q < PPK; ++q) {
;           const int pi = kk * PPK + q;
;           if (pi < NPA) stage_piece<BM, BK>(An, lda, nxt, tid, pi, wv);
;           else if (pi < NP) stage_piece<BN, BK>(Bn, ldb, nxt + ABYTES, tid, pi - NPA, wv);
;         }
;       }
;       __builtin_amdgcn_s_setprio(1);
; #pragma unroll
;       for (int mt = 0; mt < 2; ++mt)
; #pragma unroll
;         for (int nt = 0; nt < NTW; ++nt) acc[mt][nt] = mfma(fa[kk & 1][mt], fb[kk & 1][nt], acc[mt][nt]);
;       __builtin_amdgcn_s_setprio(0);
;       __builtin_amdgcn_sched_barrier(0);
;     }
;     wait_vm0();
;     __syncthreads();
.LBB0_532:
	s_and_b32 s7, s3, 0x10000
	s_xor_b32 s100, s7, 0x10000
	v_add3_u32 v194, s100, v136, v166
	v_add3_u32 v198, s100, v144, v167
	ds_read_b128 v[194:197], v194
	v_add3_u32 v202, s100, v145, v163
	ds_read_b128 v[198:201], v198
	v_add3_u32 v206, s100, v150, v164
	ds_read_b128 v[202:205], v202 offset:32768
	v_add3_u32 v210, s100, v156, v159
	ds_read_b128 v[206:209], v206 offset:32768
	v_add3_u32 v226, s100, v158, v160
	ds_read_b128 v[210:213], v210 offset:32768
	ds_read_b128 v[226:229], v226 offset:32768
	s_waitcnt lgkmcnt(6)
	s_add_i32 m0, s101, 0x8000
	v_mov_b64_e32 v[232:233], v[214:215]
	v_mfma_f32_32x32x16_bf16 v[114:129], v[170:173], v[178:181], v[114:129]
	global_load_lds_dwordx4 v[232:233], off
	v_mfma_f32_32x32x16_bf16 v[98:113], v[170:173], v[182:185], v[98:113]
	s_add_i32 m0, s101, 0xa000
	v_lshl_add_u64 v[232:233], v[214:215], 0, s[36:37]
	v_mfma_f32_32x32x16_bf16 v[82:97], v[170:173], v[186:189], v[82:97]
	global_load_lds_dwordx4 v[232:233], off
	v_mfma_f32_32x32x16_bf16 v[66:81], v[170:173], v[190:193], v[66:81]
	s_add_i32 m0, s101, 0xc000
	v_lshl_add_u64 v[232:233], v[214:215], 0, s[40:41]
	v_mfma_f32_32x32x16_bf16 v[50:65], v[174:177], v[178:181], v[50:65]
	global_load_lds_dwordx4 v[232:233], off
	v_mfma_f32_32x32x16_bf16 v[34:49], v[174:177], v[182:185], v[34:49]
	s_add_i32 m0, s101, 0xe000
	v_lshl_add_u64 v[232:233], v[214:215], 0, s[34:35]
	v_mfma_f32_32x32x16_bf16 v[18:33], v[174:177], v[186:189], v[18:33]
	global_load_lds_dwordx4 v[232:233], off
	v_mfma_f32_32x32x16_bf16 v[2:17], v[174:177], v[190:193], v[2:17]
	v_add3_u32 v170, s100, v136, v153
	v_add3_u32 v174, s100, v144, v154
	ds_read_b128 v[170:173], v170
	v_add3_u32 v178, s100, v145, v151
	ds_read_b128 v[174:177], v174
	v_add3_u32 v182, s100, v150, v152
	ds_read_b128 v[178:181], v178 offset:32768
	v_add3_u32 v186, s100, v156, v147
	ds_read_b128 v[182:185], v182 offset:32768
	v_add3_u32 v190, s100, v158, v148
	ds_read_b128 v[186:189], v186 offset:32768
	ds_read_b128 v[190:193], v190 offset:32768
	s_waitcnt lgkmcnt(6)
	v_mfma_f32_32x32x16_bf16 v[114:129], v[194:197], v[202:205], v[114:129]
	v_mfma_f32_32x32x16_bf16 v[98:113], v[194:197], v[206:209], v[98:113]
	v_mfma_f32_32x32x16_bf16 v[82:97], v[194:197], v[210:213], v[82:97]
	v_mfma_f32_32x32x16_bf16 v[66:81], v[194:197], v[226:229], v[66:81]
	v_mfma_f32_32x32x16_bf16 v[50:65], v[198:201], v[202:205], v[50:65]
	v_mfma_f32_32x32x16_bf16 v[34:49], v[198:201], v[206:209], v[34:49]
	v_mfma_f32_32x32x16_bf16 v[18:33], v[198:201], v[210:213], v[18:33]
	v_mfma_f32_32x32x16_bf16 v[2:17], v[198:201], v[226:229], v[2:17]
	v_add3_u32 v194, s100, v136, v141
	v_add3_u32 v198, s100, v144, v142
	ds_read_b128 v[194:197], v194
	v_add3_u32 v202, s100, v145, v139
	ds_read_b128 v[198:201], v198
	v_add3_u32 v206, s100, v150, v140
	ds_read_b128 v[202:205], v202 offset:32768
	v_add3_u32 v210, s100, v156, v137
	ds_read_b128 v[206:209], v206 offset:32768
	v_add3_u32 v226, s100, v158, v138
	ds_read_b128 v[210:213], v210 offset:32768
	ds_read_b128 v[226:229], v226 offset:32768
	s_waitcnt lgkmcnt(6)
	v_mfma_f32_32x32x16_bf16 v[114:129], v[170:173], v[178:181], v[114:129]
	v_mfma_f32_32x32x16_bf16 v[98:113], v[170:173], v[182:185], v[98:113]
	v_mfma_f32_32x32x16_bf16 v[82:97], v[170:173], v[186:189], v[82:97]
	v_mfma_f32_32x32x16_bf16 v[66:81], v[170:173], v[190:193], v[66:81]
	v_mfma_f32_32x32x16_bf16 v[50:65], v[174:177], v[178:181], v[50:65]
	v_mfma_f32_32x32x16_bf16 v[34:49], v[174:177], v[182:185], v[34:49]
	v_mfma_f32_32x32x16_bf16 v[18:33], v[174:177], v[186:189], v[18:33]
	v_mfma_f32_32x32x16_bf16 v[2:17], v[174:177], v[190:193], v[2:17]
	s_add_i32 s6, s6, -1
	s_add_i32 s92, s92, 64
	s_add_i32 s3, s3, 0x10000
	s_waitcnt vmcnt(0) lgkmcnt(0)
	s_barrier
	v_add3_u32 v170, s7, v136, v143
	v_add3_u32 v174, s7, v144, v146
	ds_read_b128 v[170:173], v170
	v_add3_u32 v178, s7, v145, v149
	ds_read_b128 v[174:177], v174
	v_add3_u32 v182, s7, v150, v155
	ds_read_b128 v[178:181], v178 offset:32768
	v_add3_u32 v186, s7, v156, v157
	ds_read_b128 v[182:185], v182 offset:32768
	v_add3_u32 v190, s7, v158, v168
	ds_read_b128 v[186:189], v186 offset:32768
	ds_read_b128 v[190:193], v190 offset:32768
	s_cmp_lg_u32 s6, 0
	s_cbranch_scc0 .Lk532_exit
	s_add_i32 s101, s100, s2
	s_lshl_b64 s[30:31], s[92:93], 1
	v_lshl_add_u64 v[230:231], v[130:131], 0, s[30:31]
	v_lshl_add_u64 v[214:215], v[132:133], 0, s[30:31]
	s_mov_b32 m0, s101
	v_mov_b64_e32 v[232:233], v[230:231]
	v_mfma_f32_32x32x16_bf16 v[114:129], v[194:197], v[202:205], v[114:129]
	global_load_lds_dwordx4 v[232:233], off
	v_mfma_f32_32x32x16_bf16 v[98:113], v[194:197], v[206:209], v[98:113]
	s_add_i32 m0, s101, 0x2000
	v_lshl_add_u64 v[232:233], v[230:231], 0, s[36:37]
	v_mfma_f32_32x32x16_bf16 v[82:97], v[194:197], v[210:213], v[82:97]
	global_load_lds_dwordx4 v[232:233], off
	v_mfma_f32_32x32x16_bf16 v[66:81], v[194:197], v[226:229], v[66:81]
	s_add_i32 m0, s101, 0x4000
	v_lshl_add_u64 v[232:233], v[230:231], 0, s[40:41]
	v_mfma_f32_32x32x16_bf16 v[50:65], v[198:201], v[202:205], v[50:65]
	global_load_lds_dwordx4 v[232:233], off
	v_mfma_f32_32x32x16_bf16 v[34:49], v[198:201], v[206:209], v[34:49]
	s_add_i32 m0, s101, 0x6000
	v_lshl_add_u64 v[232:233], v[230:231], 0, s[34:35]
	v_mfma_f32_32x32x16_bf16 v[18:33], v[198:201], v[210:213], v[18:33]
	global_load_lds_dwordx4 v[232:233], off
	v_mfma_f32_32x32x16_bf16 v[2:17], v[198:201], v[226:229], v[2:17]
	s_branch .LBB0_532

; DI f32x16 mfma(bf16x8 a, bf16x8 b, f32x16 c) { return __builtin_amdgcn_mfma_f32_32x32x16_bf16(a, b, c, 0, 0, 0); }
; template <int BK> DI int swz(int row) { constexpr int CPR = BK / 8; return (row / (16 / CPR)) % CPR; }
; DI void wait_vm0() { asm volatile("s_waitcnt vmcnt(0)" ::: "memory"); }
;   DI void pre(int grow0, int gcol0, int lane, int w, char* lds) { xpass(0, grow0, gcol0, lane, w, lds); }
;     ...
;   for (int kt = 0; kt < nk; ++kt) {
;     char* cur = lds + (kt & 1) * STG; char* nxt = lds + ((kt + 1) & 1) * STG;
;     const bool more = kt + 1 < nk;
;     const bf16_t* An = Ag + (kt + 1) * BK; const bf16_t* Bn = Bg + (kt + 1) * BK;
;     if (!more) epi.pre(row0 + wm * 64, col0 + wn * (32 * NTW), lane, w, lds);
;     bf16x8 fa[2][2], fb[2][NTW];
; #pragma unroll
;     for (int mt = 0; mt < 2; ++mt) { int row = wm * 64 + mt * 32 + l31; fa[0][mt] = *(const bf16x8*)(cur + row * (BK * 2) + ((hh ^ swz<BK>(row)) << 4)); }
; #pragma unroll
;     for (int nt = 0; nt < NTW; ++nt) { int row = wn * (32 * NTW) + nt * 32 + l31; fb[0][nt] = *(const bf16x8*)(cur + ABYTES + row * (BK * 2) + ((hh ^ swz<BK>(row)) << 4)); }
; #pragma unroll
;     for (int kk = 0; kk < NKK; ++kk) {
;       if (kk + 1 < NKK) {
;         const int ch = (kk + 1) * 2 + hh;
; #pragma unroll
;         for (int mt = 0; mt < 2; ++mt) { int row = wm * 64 + mt * 32 + l31; fa[(kk + 1) & 1][mt] = *(const bf16x8*)(cur + row * (BK * 2) + ((ch ^ swz<BK>(row)) << 4)); }
; #pragma unroll
;         for (int nt = 0; nt < NTW; ++nt) { int row = wn * (32 * NTW) + nt * 32 + l31; fb[(kk + 1) & 1][nt] = *(const bf16x8*)(cur + ABYTES + row * (BK * 2) + ((ch ^ swz<BK>(row)) << 4)); }
;       }
;       if (more) {
; #pragma unroll
;         for (int q = 0; q < PPK; ++q) {
;           const int pi = kk * PPK + q;
;           if (pi < NPA) stage_piece<BM, BK>(An, lda, nxt, tid, pi, wv);
;           else if (pi < NP) stage_piece<BN, BK>(Bn, ldb, nxt + ABYTES, tid, pi - NPA, wv);
;         }
;       }
;       __builtin_amdgcn_s_setprio(1);
; #pragma unroll
;       for (int mt = 0; mt < 2; ++mt)
; #pragma unroll
;         for (int nt = 0; nt < NTW; ++nt) acc[mt][nt] = mfma(fa[kk & 1][mt], fb[kk & 1][nt], acc[mt][nt]);
;       __builtin_amdgcn_s_setprio(0);
;       __builtin_amdgcn_sched_barrier(0);
;     }
;     wait_vm0();
;     __syncthreads();
.LBB0_627:
	s_and_b32 s42, s35, 0x10000
	s_xor_b32 s100, s42, 0x10000
	v_add3_u32 v190, s100, v136, v161
	v_add3_u32 v194, s100, v142, v163
	ds_read_b128 v[190:193], v190
	v_add3_u32 v198, s100, v143, v159
	ds_read_b128 v[194:197], v194
	v_add3_u32 v202, s100, v152, v160
	ds_read_b128 v[198:201], v198 offset:32768
	v_add3_u32 v206, s100, v153, v157
	ds_read_b128 v[202:205], v202 offset:32768
	v_add3_u32 v210, s100, v156, v158
	ds_read_b128 v[206:209], v206 offset:32768
	ds_read_b128 v[210:213], v210 offset:32768
	s_waitcnt lgkmcnt(6)
	s_add_i32 m0, s41, 0x8000
	v_lshl_add_u64 v[228:229], v[226:227], 0, s[28:29]
	v_mfma_f32_32x32x16_bf16 v[114:129], v[166:169], v[174:177], v[114:129]
	global_load_lds_dwordx4 v[228:229], off
	s_add_i32 m0, s41, 0xa000
	v_lshl_add_u64 v[228:229], v[226:227], 0, s[24:25]
	v_mfma_f32_32x32x16_bf16 v[98:113], v[166:169], v[178:181], v[98:113]
	v_mfma_f32_32x32x16_bf16 v[82:97], v[166:169], v[182:185], v[82:97]
	global_load_lds_dwordx4 v[228:229], off
	s_add_i32 m0, s41, 0xc000
	v_lshl_add_u64 v[228:229], v[226:227], 0, s[26:27]
	v_mfma_f32_32x32x16_bf16 v[66:81], v[166:169], v[186:189], v[66:81]
	v_mfma_f32_32x32x16_bf16 v[50:65], v[170:173], v[174:177], v[50:65]
	global_load_lds_dwordx4 v[228:229], off
	s_add_i32 m0, s41, 0xe000
	v_lshl_add_u64 v[228:229], v[226:227], 0, s[38:39]
	v_mfma_f32_32x32x16_bf16 v[34:49], v[170:173], v[178:181], v[34:49]
	v_mfma_f32_32x32x16_bf16 v[18:33], v[170:173], v[182:185], v[18:33]
	global_load_lds_dwordx4 v[228:229], off
	v_mfma_f32_32x32x16_bf16 v[2:17], v[170:173], v[186:189], v[2:17]
	v_add3_u32 v166, s100, v136, v149
	v_add3_u32 v170, s100, v142, v150
	ds_read_b128 v[166:169], v166
	v_add3_u32 v174, s100, v143, v147
	ds_read_b128 v[170:173], v170
	v_add3_u32 v178, s100, v152, v148
	ds_read_b128 v[174:177], v174 offset:32768
	v_add3_u32 v182, s100, v153, v145
	ds_read_b128 v[178:181], v178 offset:32768
	v_add3_u32 v186, s100, v156, v146
	ds_read_b128 v[182:185], v182 offset:32768
	ds_read_b128 v[186:189], v186 offset:32768
	s_waitcnt lgkmcnt(6)
	v_mfma_f32_32x32x16_bf16 v[114:129], v[190:193], v[198:201], v[114:129]
	v_mfma_f32_32x32x16_bf16 v[98:113], v[190:193], v[202:205], v[98:113]
	v_mfma_f32_32x32x16_bf16 v[82:97], v[190:193], v[206:209], v[82:97]
	v_mfma_f32_32x32x16_bf16 v[66:81], v[190:193], v[210:213], v[66:81]
	v_mfma_f32_32x32x16_bf16 v[50:65], v[194:197], v[198:201], v[50:65]
	v_mfma_f32_32x32x16_bf16 v[34:49], v[194:197], v[202:205], v[34:49]
	v_mfma_f32_32x32x16_bf16 v[18:33], v[194:197], v[206:209], v[18:33]
	v_mfma_f32_32x32x16_bf16 v[2:17], v[194:197], v[210:213], v[2:17]
	v_add3_u32 v190, s100, v136, v139
	v_add3_u32 v194, s100, v142, v140
	ds_read_b128 v[190:193], v190
	v_add3_u32 v198, s100, v143, v137
	ds_read_b128 v[194:197], v194
	v_add3_u32 v202, s100, v152, v138
	ds_read_b128 v[198:201], v198 offset:32768
	v_add3_u32 v206, s100, v153, v134
	ds_read_b128 v[202:205], v202 offset:32768
	v_add3_u32 v210, s100, v156, v135
	ds_read_b128 v[206:209], v206 offset:32768
	ds_read_b128 v[210:213], v210 offset:32768
	s_waitcnt lgkmcnt(6)
	v_mfma_f32_32x32x16_bf16 v[114:129], v[166:169], v[174:177], v[114:129]
	v_mfma_f32_32x32x16_bf16 v[98:113], v[166:169], v[178:181], v[98:113]
	v_mfma_f32_32x32x16_bf16 v[82:97], v[166:169], v[182:185], v[82:97]
	v_mfma_f32_32x32x16_bf16 v[66:81], v[166:169], v[186:189], v[66:81]
	v_mfma_f32_32x32x16_bf16 v[50:65], v[170:173], v[174:177], v[50:65]
	v_mfma_f32_32x32x16_bf16 v[34:49], v[170:173], v[178:181], v[34:49]
	v_mfma_f32_32x32x16_bf16 v[18:33], v[170:173], v[182:185], v[18:33]
	v_mfma_f32_32x32x16_bf16 v[2:17], v[170:173], v[186:189], v[2:17]
	s_add_u32 s30, s30, 0x80
	s_addc_u32 s31, s31, 0
	s_add_i32 s35, s35, 0x10000
	s_waitcnt vmcnt(0) lgkmcnt(0)
	s_barrier
	v_add3_u32 v166, s42, v136, v141
	v_add3_u32 v170, s42, v142, v144
	ds_read_b128 v[166:169], v166
	v_add3_u32 v174, s42, v143, v151
	ds_read_b128 v[170:173], v170
	v_add3_u32 v178, s42, v152, v154
	ds_read_b128 v[174:177], v174 offset:32768
	v_add3_u32 v182, s42, v153, v155
	ds_read_b128 v[178:181], v178 offset:32768
	v_add3_u32 v186, s42, v156, v164
	ds_read_b128 v[182:185], v182 offset:32768
	ds_read_b128 v[186:189], v186 offset:32768
	s_cmpk_lg_i32 s30, 0x780
	s_cbranch_scc0 .Lk627_exit
	s_add_i32 s41, s100, s34
	v_lshl_add_u64 v[214:215], v[130:131], 0, s[30:31]
	v_lshl_add_u64 v[226:227], v[132:133], 0, s[30:31]
	s_mov_b32 m0, s41
	v_lshl_add_u64 v[228:229], v[214:215], 0, s[28:29]
	v_mfma_f32_32x32x16_bf16 v[114:129], v[190:193], v[198:201], v[114:129]
	global_load_lds_dwordx4 v[228:229], off
	s_add_i32 m0, s41, 0x2000
	v_lshl_add_u64 v[228:229], v[214:215], 0, s[24:25]
	v_mfma_f32_32x32x16_bf16 v[98:113], v[190:193], v[202:205], v[98:113]
	v_mfma_f32_32x32x16_bf16 v[82:97], v[190:193], v[206:209], v[82:97]
	global_load_lds_dwordx4 v[228:229], off
	s_add_i32 m0, s41, 0x4000
	v_lshl_add_u64 v[228:229], v[214:215], 0, s[26:27]
	v_mfma_f32_32x32x16_bf16 v[66:81], v[190:193], v[210:213], v[66:81]
	v_mfma_f32_32x32x16_bf16 v[50:65], v[194:197], v[198:201], v[50:65]
	global_load_lds_dwordx4 v[228:229], off
	s_add_i32 m0, s41, 0x6000
	v_lshl_add_u64 v[228:229], v[214:215], 0, s[38:39]
	v_mfma_f32_32x32x16_bf16 v[34:49], v[194:197], v[202:205], v[34:49]
	v_mfma_f32_32x32x16_bf16 v[18:33], v[194:197], v[206:209], v[18:33]
	global_load_lds_dwordx4 v[228:229], off
	v_mfma_f32_32x32x16_bf16 v[2:17], v[194:197], v[210:213], v[2:17]
	s_branch .LBB0_627
